# v14: v8 + GEMM K-loop LDS-DMA loads use SGPR base + 32-bit VGPR offset (drops the per-load 64-bit VALU address add) in 116 of 220 sites
# speedup vs baseline: 1.0111x; 1.0033x over previous
; #define PG8_WAIT_V(n) asm volatile("s_waitcnt vmcnt(" #n ")" ::: "memory")
; #define PG8_BAR __builtin_amdgcn_s_barrier()
;     ...
;     if constexpr (SP2) {
;         PG8_STAGE(PG8_SB(0, 0), cB, voffB); PG8_STAGE(PG8_SB(0, 1), cB + hstep, voffB); PG8_STAGE(PG8_SA(0, 0), cA, voffA); PG8_STAGE(PG8_SA(0, 1), cA + hstepA, voffA);
;         if (wr == 1) PG8_BAR;
;         PG8_WAIT_V(2); PG8_BAR;
;         PG8_STAGE(PG8_SB(1, 0), cB + kstep, voffB); PG8_STAGE(PG8_SA(1, 0), cA + kstep, voffA); PG8_STAGE(PG8_SB(1, 1), cB + hstep + kstep, voffB);
;         PG8_WAIT_V(6); PG8_BAR;
.LBB0_311:
	v_readlane_b32 s12, v254, 11
	v_readlane_b32 s20, v254, 13
	v_readlane_b32 s13, v254, 12
	v_readlane_b32 s21, v254, 14
	s_and_b32 s5, s5, 3
	s_and_b32 s85, s93, 0xffff
	s_and_b32 s9, s13, 0xffff
	s_and_b32 s13, s21, 0xffff
	s_ashr_i32 s45, s88, 31
	s_ashr_i32 s46, s90, 31
	s_lshl_b32 s47, s8, 6
	s_lshl_b32 s7, s8, 13
	s_lshl_b32 s48, s5, 5
	s_lshl_b32 s16, s5, 12
	s_add_u32 s10, s30, 0x80
	s_addc_u32 s11, s31, 0
	s_add_i32 m0, s29, 0x18000
	s_waitcnt vmcnt(2)
	s_barrier
	global_load_lds_dwordx4 v144, s[10:11]
	s_add_i32 m0, s29, 0x1a000
	v_lshl_add_u64 v[2:3], s[10:11], 0, v[148:149]
	s_add_u32 s10, s14, 0x80
	s_addc_u32 s11, s15, 0
	s_add_i32 s49, s29, 0x8000
	global_load_lds_dwordx4 v[2:3], off
	s_mov_b32 m0, s49
	s_add_i32 s50, s29, 0xa000
	global_load_lds_dwordx4 v252, s[10:11]
	v_lshl_add_u64 v[2:3], s[10:11], 0, v[146:147]
	s_add_u32 s10, s30, 0x80080
	s_mov_b32 m0, s50
	s_addc_u32 s11, s31, 0
	global_load_lds_dwordx4 v[2:3], off
	s_add_i32 m0, s29, 0x1c000
	global_load_lds_dwordx4 v144, s[10:11]
	s_add_i32 m0, s29, 0x1e000
	v_and_b32_e32 v1, 48, v0
	global_load_lds_dwordx4 v148, s[10:11]
	v_lshlrev_b32_e32 v2, 6, v0
	s_movk_i32 s17, 0x3c0
	v_lshlrev_b32_e32 v0, 2, v0
	v_and_or_b32 v1, v2, s17, v1
	v_and_b32_e32 v0, 32, v0
	s_waitcnt vmcnt(6)
	s_cmpk_lt_u32 s4, 0x100
	s_mov_b32 s87, 0x20000
	v_bitop3_b32 v2, v1, s7, v0 bitop3:0xde
	v_bitop3_b32 v154, s16, v1, v0 bitop3:0xf6
	s_cselect_b64 s[16:17], -1, 0
	s_add_i32 s53, 0, 0x10000
	s_add_i32 s54, 0, 0x14000
	s_brev_b32 s86, 36
	s_mov_b32 s8, s12
	s_mov_b32 s10, 0x400000
	s_mov_b32 s11, s87
	s_mov_b32 s12, s20
	s_lshl_b32 s51, s5, 6
	s_movk_i32 s52, 0x241
	v_add_u32_e32 v155, s53, v154
	v_add_u32_e32 v156, s54, v154
	v_add_u32_e32 v157, 0, v2
	v_mov_b32_e32 v158, 0x7f7f7f7f
	s_mov_b32 s18, 0x3c800000
	v_mov_b32_e32 v159, 0x1fcf
	s_barrier
	s_branch .LBB0_314

; #define PG8_WAIT_V(n) asm volatile("s_waitcnt vmcnt(" #n ")" ::: "memory")
; #define PG8_WAIT_L(n) asm volatile("s_waitcnt lgkmcnt(" #n ")" ::: "memory")
; #define PG8_BAR __builtin_amdgcn_s_barrier()
; #define PG8_SCHED __builtin_amdgcn_sched_barrier(0)
;     ...
;             PG8_LDB(B0, 0, 0); PG8_LDB(B1, 0, 1); PG8_SCHED; PG8_LDA(At, 0, 0); PG8_STAGE(PG8_SA(1, 1), a1 + hstepA, voffA);
;             PG8_WAIT_V(8); PG8_WAIT_L(0); PG8_BAR; PG8_MMA(0, 0, At, B0); PG8_MMA(0, 1, At, B1); PG8_BAR; PG8_SCHED;
;             if constexpr (!HALFU) PG8_LDA(At, 0, 1); PG8_STAGE(PG8_SB(0, 0), b2, voffB); PG8_STAGE(PG8_SB(0, 1), b2 + hstep, voffB); PG8_STAGE(PG8_SA(0, 0), a2, voffA);
;             PG8_WAIT_V(8); PG8_WAIT_L(0); PG8_BAR; if constexpr (!HALFU) { PG8_MMA(1, 0, At, B0); PG8_MMA(1, 1, At, B1); } PG8_BAR; PG8_SCHED;
.LBB0_317:
	ds_read_b128 v[128:131], v155
	ds_read_b128 v[132:135], v155 offset:1024
	ds_read_b128 v[164:167], v155 offset:2048
	ds_read_b128 v[168:171], v155 offset:3072
	ds_read_b128 v[172:175], v156
	ds_read_b128 v[176:179], v156 offset:1024
	ds_read_b128 v[180:183], v156 offset:2048
	ds_read_b128 v[184:187], v156 offset:3072
	s_add_u32 s30, s14, 0x100
	s_addc_u32 s31, s15, 0
	s_cmp_eq_u32 s58, 28
	s_cselect_b32 s38, s23, s30
	s_cselect_b32 s39, s7, s31
	s_cselect_b32 s36, s55, s56
	s_cselect_b32 s37, s21, s57
	s_add_u32 s34, s38, 0x80
	s_addc_u32 s35, s39, 0
	s_add_u32 s14, s14, 0x80080
	s_addc_u32 s15, s15, 0
	s_add_i32 m0, s29, 0xc000
	ds_read_b128 v[188:191], v157
	ds_read_b128 v[192:195], v157 offset:1024
	ds_read_b128 v[196:199], v157 offset:2048
	ds_read_b128 v[200:203], v157 offset:3072
	ds_read_b128 v[204:207], v157 offset:4096
	ds_read_b128 v[208:211], v157 offset:5120
	ds_read_b128 v[212:215], v157 offset:6144
	ds_read_b128 v[216:219], v157 offset:7168
	global_load_lds_dwordx4 v252, s[14:15]
	s_add_i32 m0, s29, 0xe000
	s_nop 0
	global_load_lds_dwordx4 v146, s[14:15]
	s_waitcnt vmcnt(8)
	s_waitcnt lgkmcnt(0)
	s_barrier
	s_setprio 1
	s_waitcnt lgkmcnt(0)
	v_mfma_scale_f32_16x16x128_f8f6f4 v[124:127], v[128:135], v[188:195], v[124:127], v158, v158 op_sel_hi:[0,0,0]
	v_mfma_scale_f32_16x16x128_f8f6f4 v[120:123], v[164:171], v[188:195], v[120:123], v158, v158 op_sel_hi:[0,0,0]
	v_mfma_scale_f32_16x16x128_f8f6f4 v[108:111], v[128:135], v[196:203], v[108:111], v158, v158 op_sel_hi:[0,0,0]
	v_mfma_scale_f32_16x16x128_f8f6f4 v[104:107], v[164:171], v[196:203], v[104:107], v158, v158 op_sel_hi:[0,0,0]
	v_mfma_scale_f32_16x16x128_f8f6f4 v[136:139], v[128:135], v[204:211], v[92:95], v158, v158 op_sel_hi:[0,0,0]
	v_mfma_scale_f32_16x16x128_f8f6f4 v[220:223], v[164:171], v[204:211], v[88:91], v158, v158 op_sel_hi:[0,0,0]
	v_mfma_scale_f32_16x16x128_f8f6f4 v[224:227], v[128:135], v[212:219], v[76:79], v158, v158 op_sel_hi:[0,0,0]
	v_mfma_scale_f32_16x16x128_f8f6f4 v[228:231], v[164:171], v[212:219], v[72:75], v158, v158 op_sel_hi:[0,0,0]
	s_setprio 0
	s_setprio 1
	v_mfma_scale_f32_16x16x128_f8f6f4 v[116:119], v[172:179], v[188:195], v[116:119], v158, v158 op_sel_hi:[0,0,0]
	v_mfma_scale_f32_16x16x128_f8f6f4 v[112:115], v[180:187], v[188:195], v[112:115], v158, v158 op_sel_hi:[0,0,0]
	v_mfma_scale_f32_16x16x128_f8f6f4 v[100:103], v[172:179], v[196:203], v[100:103], v158, v158 op_sel_hi:[0,0,0]
	v_mfma_scale_f32_16x16x128_f8f6f4 v[96:99], v[180:187], v[196:203], v[96:99], v158, v158 op_sel_hi:[0,0,0]
	v_mfma_scale_f32_16x16x128_f8f6f4 v[188:191], v[172:179], v[204:211], v[84:87], v158, v158 op_sel_hi:[0,0,0]
	v_mfma_scale_f32_16x16x128_f8f6f4 v[192:195], v[180:187], v[204:211], v[80:83], v158, v158 op_sel_hi:[0,0,0]
	v_mfma_scale_f32_16x16x128_f8f6f4 v[196:199], v[172:179], v[212:219], v[68:71], v158, v158 op_sel_hi:[0,0,0]
	v_mfma_scale_f32_16x16x128_f8f6f4 v[200:203], v[180:187], v[212:219], v[64:67], v158, v158 op_sel_hi:[0,0,0]
	s_setprio 0
	s_barrier
	s_add_i32 s14, s53, s40
	s_mov_b32 m0, s14
	s_nop 1
	ds_read_b128 v[64:67], v157 offset:16384
	ds_read_b128 v[68:71], v157 offset:17408
	ds_read_b128 v[72:75], v157 offset:18432
	ds_read_b128 v[76:79], v157 offset:19456
	ds_read_b128 v[80:83], v157 offset:20480
	ds_read_b128 v[84:87], v157 offset:21504
	ds_read_b128 v[88:91], v157 offset:22528
	ds_read_b128 v[92:95], v157 offset:23552
	global_load_lds_dwordx4 v144, s[36:37]
	s_add_i32 m0, s14, 0x2000
	s_add_u32 s14, s36, 0x80000
	s_addc_u32 s15, s37, 0
	s_add_i32 s59, s54, s40
	global_load_lds_dwordx4 v148, s[36:37]
	s_mov_b32 m0, s59
	s_nop 0
	global_load_lds_dwordx4 v144, s[14:15]
	s_add_i32 m0, s59, 0x2000
	s_nop 0
	global_load_lds_dwordx4 v148, s[14:15]
	s_mov_b32 m0, s29
	s_nop 0
	global_load_lds_dwordx4 v252, s[38:39]
	s_mov_b32 m0, s41
	s_nop 0
	global_load_lds_dwordx4 v146, s[38:39]
	s_waitcnt vmcnt(8)
	s_waitcnt lgkmcnt(0)
	s_barrier
	s_setprio 1
	s_waitcnt lgkmcnt(0)
	v_mfma_scale_f32_16x16x128_f8f6f4 v[60:63], v[128:135], v[64:71], v[60:63], v158, v158 op_sel_hi:[0,0,0]
	v_mfma_scale_f32_16x16x128_f8f6f4 v[56:59], v[164:171], v[64:71], v[56:59], v158, v158 op_sel_hi:[0,0,0]
	v_mfma_scale_f32_16x16x128_f8f6f4 v[204:207], v[128:135], v[72:79], v[44:47], v158, v158 op_sel_hi:[0,0,0]
	v_mfma_scale_f32_16x16x128_f8f6f4 v[208:211], v[164:171], v[72:79], v[40:43], v158, v158 op_sel_hi:[0,0,0]
	v_mfma_scale_f32_16x16x128_f8f6f4 v[212:215], v[128:135], v[80:87], v[28:31], v158, v158 op_sel_hi:[0,0,0]
	v_mfma_scale_f32_16x16x128_f8f6f4 v[216:219], v[164:171], v[80:87], v[24:27], v158, v158 op_sel_hi:[0,0,0]
	v_mfma_scale_f32_16x16x128_f8f6f4 v[232:235], v[128:135], v[88:95], v[12:15], v158, v158 op_sel_hi:[0,0,0]
	v_mfma_scale_f32_16x16x128_f8f6f4 v[236:239], v[164:171], v[88:95], v[8:11], v158, v158 op_sel_hi:[0,0,0]
	s_setprio 0
	s_setprio 1
	v_mfma_scale_f32_16x16x128_f8f6f4 v[52:55], v[172:179], v[64:71], v[52:55], v158, v158 op_sel_hi:[0,0,0]
	v_mfma_scale_f32_16x16x128_f8f6f4 v[48:51], v[180:187], v[64:71], v[48:51], v158, v158 op_sel_hi:[0,0,0]
	v_mfma_scale_f32_16x16x128_f8f6f4 v[240:243], v[172:179], v[72:79], v[36:39], v158, v158 op_sel_hi:[0,0,0]
	v_mfma_scale_f32_16x16x128_f8f6f4 v[244:247], v[180:187], v[72:79], v[32:35], v158, v158 op_sel_hi:[0,0,0]
	v_mfma_scale_f32_16x16x128_f8f6f4 v[248:251], v[172:179], v[80:87], v[20:23], v158, v158 op_sel_hi:[0,0,0]
	v_mfma_scale_f32_16x16x128_f8f6f4 v[150:153], v[180:187], v[80:87], v[16:19], v158, v158 op_sel_hi:[0,0,0]
	v_mfma_scale_f32_16x16x128_f8f6f4 v[160:163], v[172:179], v[88:95], v[4:7], v158, v158 op_sel_hi:[0,0,0]
	v_mfma_scale_f32_16x16x128_f8f6f4 v[140:143], v[180:187], v[88:95], v[0:3], v158, v158 op_sel_hi:[0,0,0]
	s_setprio 0
	s_barrier
; #define PG8_WAIT_V(n) asm volatile("s_waitcnt vmcnt(" #n ")" ::: "memory")
; #define PG8_WAIT_L(n) asm volatile("s_waitcnt lgkmcnt(" #n ")" ::: "memory")
; #define PG8_BAR __builtin_amdgcn_s_barrier()
; #define PG8_SCHED __builtin_amdgcn_sched_barrier(0)
;     ...
;             PG8_LDB(B0, 1, 0); PG8_LDB(B1, 1, 1); PG8_SCHED; PG8_LDA(At, 1, 0); PG8_STAGE(PG8_SA(0, 1), a2 + hstepA, voffA);
;             PG8_WAIT_V(8); PG8_WAIT_L(0); PG8_BAR; PG8_MMA(0, 0, At, B0); PG8_MMA(0, 1, At, B1); PG8_BAR; PG8_SCHED;
;             if constexpr (!HALFU) PG8_LDA(At, 1, 1); PG8_STAGE(PG8_SB(1, 0), b3, voffB); PG8_STAGE(PG8_SB(1, 1), b3 + hstep, voffB); PG8_STAGE(PG8_SA(1, 0), a3, voffA);
;             PG8_WAIT_V(8); PG8_WAIT_L(0); PG8_BAR; if constexpr (!HALFU) { PG8_MMA(1, 0, At, B0); PG8_MMA(1, 1, At, B1); } PG8_BAR; PG8_SCHED;
	s_add_i32 s59, 0, 0x18000
	v_add_u32_e32 v8, s59, v154
	s_add_i32 s60, 0, 0x1c000
	s_nop 1
	ds_read_b128 v[0:3], v8
	ds_read_b128 v[4:7], v8 offset:1024
	ds_read_b128 v[16:19], v8 offset:2048
	ds_read_b128 v[20:23], v8 offset:3072
	v_add_u32_e32 v8, s60, v154
	ds_read_b128 v[128:131], v8
	ds_read_b128 v[132:135], v8 offset:1024
	ds_read_b128 v[164:167], v8 offset:2048
	ds_read_b128 v[168:171], v8 offset:3072
	s_add_u32 s14, s38, 0x80000
	s_addc_u32 s15, s39, 0
	s_mov_b32 m0, s42
	ds_read_b128 v[8:11], v157 offset:32768
	ds_read_b128 v[12:15], v157 offset:33792
	ds_read_b128 v[24:27], v157 offset:34816
	ds_read_b128 v[28:31], v157 offset:35840
	ds_read_b128 v[32:35], v157 offset:36864
	ds_read_b128 v[36:39], v157 offset:37888
	ds_read_b128 v[40:43], v157 offset:38912
	ds_read_b128 v[44:47], v157 offset:39936
	global_load_lds_dwordx4 v252, s[14:15]
	s_mov_b32 m0, s43
	s_nop 0
	global_load_lds_dwordx4 v146, s[14:15]
	s_waitcnt vmcnt(8)
	s_waitcnt lgkmcnt(0)
	s_barrier
	s_setprio 1
	s_waitcnt lgkmcnt(0)
	v_mfma_scale_f32_16x16x128_f8f6f4 v[124:127], v[0:7], v[8:15], v[124:127], v158, v158 op_sel_hi:[0,0,0]
	v_mfma_scale_f32_16x16x128_f8f6f4 v[120:123], v[16:23], v[8:15], v[120:123], v158, v158 op_sel_hi:[0,0,0]
	v_mfma_scale_f32_16x16x128_f8f6f4 v[108:111], v[0:7], v[24:31], v[108:111], v158, v158 op_sel_hi:[0,0,0]
	v_mfma_scale_f32_16x16x128_f8f6f4 v[104:107], v[16:23], v[24:31], v[104:107], v158, v158 op_sel_hi:[0,0,0]
	v_mfma_scale_f32_16x16x128_f8f6f4 v[92:95], v[0:7], v[32:39], v[136:139], v158, v158 op_sel_hi:[0,0,0]
	v_mfma_scale_f32_16x16x128_f8f6f4 v[88:91], v[16:23], v[32:39], v[220:223], v158, v158 op_sel_hi:[0,0,0]
	v_mfma_scale_f32_16x16x128_f8f6f4 v[76:79], v[0:7], v[40:47], v[224:227], v158, v158 op_sel_hi:[0,0,0]
	v_mfma_scale_f32_16x16x128_f8f6f4 v[72:75], v[16:23], v[40:47], v[228:231], v158, v158 op_sel_hi:[0,0,0]
	s_setprio 0
	s_setprio 1
	v_mfma_scale_f32_16x16x128_f8f6f4 v[116:119], v[128:135], v[8:15], v[116:119], v158, v158 op_sel_hi:[0,0,0]
	v_mfma_scale_f32_16x16x128_f8f6f4 v[112:115], v[164:171], v[8:15], v[112:115], v158, v158 op_sel_hi:[0,0,0]
	v_mfma_scale_f32_16x16x128_f8f6f4 v[100:103], v[128:135], v[24:31], v[100:103], v158, v158 op_sel_hi:[0,0,0]
	v_mfma_scale_f32_16x16x128_f8f6f4 v[96:99], v[164:171], v[24:31], v[96:99], v158, v158 op_sel_hi:[0,0,0]
	v_mfma_scale_f32_16x16x128_f8f6f4 v[84:87], v[128:135], v[32:39], v[188:191], v158, v158 op_sel_hi:[0,0,0]
	v_mfma_scale_f32_16x16x128_f8f6f4 v[80:83], v[164:171], v[32:39], v[192:195], v158, v158 op_sel_hi:[0,0,0]
	v_mfma_scale_f32_16x16x128_f8f6f4 v[68:71], v[128:135], v[40:47], v[196:199], v158, v158 op_sel_hi:[0,0,0]
	v_mfma_scale_f32_16x16x128_f8f6f4 v[64:67], v[164:171], v[40:47], v[200:203], v158, v158 op_sel_hi:[0,0,0]
	s_setprio 0
	s_barrier
	s_add_u32 s14, s36, 0x80
	s_addc_u32 s15, s37, 0
	s_add_i32 s38, s59, s40
	s_mov_b32 m0, s38
	ds_read_b128 v[32:35], v157 offset:49152
	ds_read_b128 v[36:39], v157 offset:50176
	ds_read_b128 v[172:175], v157 offset:51200
	ds_read_b128 v[176:179], v157 offset:52224
	ds_read_b128 v[180:183], v157 offset:53248
	ds_read_b128 v[184:187], v157 offset:54272
	ds_read_b128 v[188:191], v157 offset:55296
	ds_read_b128 v[192:195], v157 offset:56320
	global_load_lds_dwordx4 v144, s[14:15]
	s_add_i32 m0, s38, 0x2000
	v_lshl_add_u64 v[8:9], s[14:15], 0, v[148:149]
	s_add_u32 s14, s36, 0x80080
	s_addc_u32 s15, s37, 0
	s_add_i32 s36, s60, s40
	global_load_lds_dwordx4 v[8:9], off
	s_mov_b32 m0, s36
	s_nop 0
	global_load_lds_dwordx4 v144, s[14:15]
	s_add_i32 m0, s36, 0x2000
	s_nop 0
	global_load_lds_dwordx4 v148, s[14:15]
	s_mov_b32 m0, s49
	s_nop 0
	global_load_lds_dwordx4 v252, s[34:35]
	s_mov_b32 m0, s50
	s_nop 0
	global_load_lds_dwordx4 v146, s[34:35]
	s_waitcnt vmcnt(8)
	s_waitcnt lgkmcnt(0)
	s_barrier
	s_setprio 1
	s_waitcnt lgkmcnt(0)
	v_mfma_scale_f32_16x16x128_f8f6f4 v[60:63], v[0:7], v[32:39], v[60:63], v158, v158 op_sel_hi:[0,0,0]
	v_mfma_scale_f32_16x16x128_f8f6f4 v[56:59], v[16:23], v[32:39], v[56:59], v158, v158 op_sel_hi:[0,0,0]
	v_mfma_scale_f32_16x16x128_f8f6f4 v[44:47], v[0:7], v[172:179], v[204:207], v158, v158 op_sel_hi:[0,0,0]
	v_mfma_scale_f32_16x16x128_f8f6f4 v[40:43], v[16:23], v[172:179], v[208:211], v158, v158 op_sel_hi:[0,0,0]
	v_mfma_scale_f32_16x16x128_f8f6f4 v[28:31], v[0:7], v[180:187], v[212:215], v158, v158 op_sel_hi:[0,0,0]
	v_mfma_scale_f32_16x16x128_f8f6f4 v[24:27], v[16:23], v[180:187], v[216:219], v158, v158 op_sel_hi:[0,0,0]
	v_mfma_scale_f32_16x16x128_f8f6f4 v[12:15], v[0:7], v[188:195], v[232:235], v158, v158 op_sel_hi:[0,0,0]
	v_mfma_scale_f32_16x16x128_f8f6f4 v[8:11], v[16:23], v[188:195], v[236:239], v158, v158 op_sel_hi:[0,0,0]
	s_setprio 0
	s_setprio 1
	v_mfma_scale_f32_16x16x128_f8f6f4 v[52:55], v[128:135], v[32:39], v[52:55], v158, v158 op_sel_hi:[0,0,0]
	v_mfma_scale_f32_16x16x128_f8f6f4 v[48:51], v[164:171], v[32:39], v[48:51], v158, v158 op_sel_hi:[0,0,0]
	v_mfma_scale_f32_16x16x128_f8f6f4 v[36:39], v[128:135], v[172:179], v[240:243], v158, v158 op_sel_hi:[0,0,0]
	v_mfma_scale_f32_16x16x128_f8f6f4 v[32:35], v[164:171], v[172:179], v[244:247], v158, v158 op_sel_hi:[0,0,0]
	v_mfma_scale_f32_16x16x128_f8f6f4 v[20:23], v[128:135], v[180:187], v[248:251], v158, v158 op_sel_hi:[0,0,0]
	v_mfma_scale_f32_16x16x128_f8f6f4 v[16:19], v[164:171], v[180:187], v[150:153], v158, v158 op_sel_hi:[0,0,0]
	v_mfma_scale_f32_16x16x128_f8f6f4 v[4:7], v[128:135], v[188:195], v[160:163], v158, v158 op_sel_hi:[0,0,0]
	v_mfma_scale_f32_16x16x128_f8f6f4 v[0:3], v[164:171], v[188:195], v[140:143], v158, v158 op_sel_hi:[0,0,0]
	s_setprio 0
	s_barrier
	s_add_i32 s58, s58, 2
	s_add_u32 s56, s56, 0x100
	s_addc_u32 s57, s57, 0
	s_cmp_gt_u32 s58, 29
	s_mov_b64 s[14:15], s[30:31]
	s_cbranch_scc0 .LBB0_317
	s_and_b64 vcc, exec, s[16:17]
	s_cbranch_vccz .LBB0_320
	s_barrier

; #define PG8_WAIT_V(n) asm volatile("s_waitcnt vmcnt(" #n ")" ::: "memory")
; #define PG8_BAR __builtin_amdgcn_s_barrier()
;     ...
;     if constexpr (SP2) {
;         PG8_STAGE(PG8_SB(0, 0), cB, voffB); PG8_STAGE(PG8_SB(0, 1), cB + hstep, voffB); PG8_STAGE(PG8_SA(0, 0), cA, voffA); PG8_STAGE(PG8_SA(0, 1), cA + hstepA, voffA);
;         if (wr == 1) PG8_BAR;
;         PG8_WAIT_V(2); PG8_BAR;
;         PG8_STAGE(PG8_SB(1, 0), cB + kstep, voffB); PG8_STAGE(PG8_SA(1, 0), cA + kstep, voffA); PG8_STAGE(PG8_SB(1, 1), cB + hstep + kstep, voffB);
;         PG8_WAIT_V(6); PG8_BAR;
.LBB0_532:
	s_lshl_b32 s6, s6, 5
	s_and_b32 s52, s6, 0x60
	s_and_b32 s13, s35, 0xffff
	s_ashr_i32 s50, s88, 31
	s_waitcnt lgkmcnt(0)
	s_and_b32 s9, s9, 0xffff
	s_lshl_b32 s51, s7, 6
	s_lshl_b32 s16, s7, 13
	s_lshl_b32 s18, s52, 7
	s_add_u32 s6, s30, 0x80
	s_addc_u32 s7, s31, 0
	s_add_i32 m0, s45, 0x18000
	s_waitcnt vmcnt(2)
	s_barrier
	global_load_lds_dwordx4 v128, s[6:7]
	s_add_i32 m0, s45, 0x1a000
	v_lshl_add_u64 v[2:3], s[6:7], 0, v[130:131]
	s_add_u32 s6, s28, 0x80
	s_addc_u32 s7, s29, 0
	s_add_i32 s53, s45, 0x8000
	global_load_lds_dwordx4 v[2:3], off
	s_mov_b32 m0, s53
	s_add_i32 s54, s45, 0xa000
	global_load_lds_dwordx4 v128, s[6:7]
	v_lshl_add_u64 v[2:3], s[6:7], 0, v[130:131]
	s_add_u32 s6, s30, 0x40080
	s_mov_b32 m0, s54
	s_addc_u32 s7, s31, 0
	global_load_lds_dwordx4 v[2:3], off
	s_add_i32 m0, s45, 0x1c000
	global_load_lds_dwordx4 v128, s[6:7]
	s_add_i32 m0, s45, 0x1e000
	s_sext_i32_i8 s15, s4
	global_load_lds_dwordx4 v130, s[6:7]
	v_and_b32_e32 v1, 48, v0
	v_lshlrev_b32_e32 v2, 6, v0
	s_movk_i32 s4, 0x3c0
	v_lshlrev_b32_e32 v0, 2, v0
	v_and_or_b32 v1, v2, s4, v1
	v_and_b32_e32 v0, 32, v0
	s_waitcnt vmcnt(6)
	s_cmpk_lt_u32 s5, 0x100
	v_bitop3_b32 v2, v1, s16, v0 bitop3:0xde
	v_bitop3_b32 v136, s18, v1, v0 bitop3:0xf6
	s_cselect_b64 s[6:7], -1, 0
	s_add_i32 s55, 0, 0x10000
	s_add_i32 s56, 0, 0x14000
	s_mov_b32 s12, s34
	s_mov_b32 s11, 0x20000
	s_brev_b32 s10, 8
	v_mov_b64_e32 v[132:133], 0x400
	v_mov_b64_e32 v[134:135], 0x3ff
	v_add_u32_e32 v137, s55, v136
	v_add_u32_e32 v138, s56, v136
	v_add_u32_e32 v139, 0, v2
	v_mov_b32_e32 v140, 0x7f7f7f7f
	s_mov_b32 s16, 0x3fb504f3
	s_mov_b32 s18, 0x3a800000
	s_barrier
	s_branch .LBB0_535

; #define PG8_WAIT_V(n) asm volatile("s_waitcnt vmcnt(" #n ")" ::: "memory")
; #define PG8_WAIT_L(n) asm volatile("s_waitcnt lgkmcnt(" #n ")" ::: "memory")
; #define PG8_BAR __builtin_amdgcn_s_barrier()
; #define PG8_SCHED __builtin_amdgcn_sched_barrier(0)
;     ...
;             PG8_LDB(B0, 0, 0); PG8_LDB(B1, 0, 1); PG8_SCHED; PG8_LDA(At, 0, 0); PG8_STAGE(PG8_SA(1, 1), a1 + hstepA, voffA);
;             PG8_WAIT_V(8); PG8_WAIT_L(0); PG8_BAR; PG8_MMA(0, 0, At, B0); PG8_MMA(0, 1, At, B1); PG8_BAR; PG8_SCHED;
;             if constexpr (!HALFU) PG8_LDA(At, 0, 1); PG8_STAGE(PG8_SB(0, 0), b2, voffB); PG8_STAGE(PG8_SB(0, 1), b2 + hstep, voffB); PG8_STAGE(PG8_SA(0, 0), a2, voffA);
;             PG8_WAIT_V(8); PG8_WAIT_L(0); PG8_BAR; if constexpr (!HALFU) { PG8_MMA(1, 0, At, B0); PG8_MMA(1, 1, At, B1); } PG8_BAR; PG8_SCHED;
.LBB0_542:
	ds_read_b128 v[142:145], v137
	ds_read_b128 v[146:149], v137 offset:1024
	ds_read_b128 v[150:153], v137 offset:2048
	ds_read_b128 v[154:157], v137 offset:3072
	ds_read_b128 v[158:161], v138
	ds_read_b128 v[162:165], v138 offset:1024
	ds_read_b128 v[166:169], v138 offset:2048
	ds_read_b128 v[170:173], v138 offset:3072
	s_add_u32 s30, s28, 0x100
	s_addc_u32 s31, s29, 0
	s_cmp_eq_u32 s61, 12
	s_cselect_b32 s40, s57, s30
	s_cselect_b32 s41, s23, s31
	s_cselect_b32 s38, s58, s59
	s_cselect_b32 s39, s21, s60
	s_add_u32 s36, s40, 0x80
	s_addc_u32 s37, s41, 0
	s_add_u32 s28, s28, 0x40080
	s_addc_u32 s29, s29, 0
	s_add_i32 m0, s45, 0xc000
	ds_read_b128 v[174:177], v139
	ds_read_b128 v[178:181], v139 offset:1024
	ds_read_b128 v[182:185], v139 offset:2048
	ds_read_b128 v[186:189], v139 offset:3072
	ds_read_b128 v[190:193], v139 offset:4096
	ds_read_b128 v[194:197], v139 offset:5120
	ds_read_b128 v[198:201], v139 offset:6144
	ds_read_b128 v[202:205], v139 offset:7168
	global_load_lds_dwordx4 v128, s[28:29]
	s_add_i32 m0, s45, 0xe000
	s_nop 0
	global_load_lds_dwordx4 v130, s[28:29]
	s_waitcnt vmcnt(8)
	s_waitcnt lgkmcnt(0)
	s_barrier
	s_setprio 1
	s_waitcnt lgkmcnt(0)
	v_mfma_scale_f32_16x16x128_f8f6f4 v[124:127], v[142:149], v[174:181], v[124:127], v140, v140 op_sel_hi:[0,0,0]
	v_mfma_scale_f32_16x16x128_f8f6f4 v[120:123], v[150:157], v[174:181], v[120:123], v140, v140 op_sel_hi:[0,0,0]
	v_mfma_scale_f32_16x16x128_f8f6f4 v[108:111], v[142:149], v[182:189], v[108:111], v140, v140 op_sel_hi:[0,0,0]
	v_mfma_scale_f32_16x16x128_f8f6f4 v[104:107], v[150:157], v[182:189], v[104:107], v140, v140 op_sel_hi:[0,0,0]
	v_mfma_scale_f32_16x16x128_f8f6f4 v[96:99], v[142:149], v[190:197], v[96:99], v140, v140 op_sel_hi:[0,0,0]
	v_mfma_scale_f32_16x16x128_f8f6f4 v[206:209], v[150:157], v[190:197], v[88:91], v140, v140 op_sel_hi:[0,0,0]
	v_mfma_scale_f32_16x16x128_f8f6f4 v[210:213], v[142:149], v[198:205], v[80:83], v140, v140 op_sel_hi:[0,0,0]
	v_mfma_scale_f32_16x16x128_f8f6f4 v[214:217], v[150:157], v[198:205], v[72:75], v140, v140 op_sel_hi:[0,0,0]
	s_setprio 0
	s_setprio 1
	v_mfma_scale_f32_16x16x128_f8f6f4 v[116:119], v[158:165], v[174:181], v[116:119], v140, v140 op_sel_hi:[0,0,0]
	v_mfma_scale_f32_16x16x128_f8f6f4 v[112:115], v[166:173], v[174:181], v[112:115], v140, v140 op_sel_hi:[0,0,0]
	v_mfma_scale_f32_16x16x128_f8f6f4 v[100:103], v[158:165], v[182:189], v[100:103], v140, v140 op_sel_hi:[0,0,0]
	v_mfma_scale_f32_16x16x128_f8f6f4 v[174:177], v[166:173], v[182:189], v[92:95], v140, v140 op_sel_hi:[0,0,0]
	v_mfma_scale_f32_16x16x128_f8f6f4 v[178:181], v[158:165], v[190:197], v[84:87], v140, v140 op_sel_hi:[0,0,0]
	v_mfma_scale_f32_16x16x128_f8f6f4 v[182:185], v[166:173], v[190:197], v[76:79], v140, v140 op_sel_hi:[0,0,0]
	v_mfma_scale_f32_16x16x128_f8f6f4 v[186:189], v[158:165], v[198:205], v[68:71], v140, v140 op_sel_hi:[0,0,0]
	v_mfma_scale_f32_16x16x128_f8f6f4 v[190:193], v[166:173], v[198:205], v[64:67], v140, v140 op_sel_hi:[0,0,0]
	s_setprio 0
	s_barrier
	s_add_i32 s28, s55, s43
	s_mov_b32 m0, s28
	s_nop 1
	ds_read_b128 v[64:67], v139 offset:16384
	ds_read_b128 v[68:71], v139 offset:17408
	ds_read_b128 v[72:75], v139 offset:18432
	ds_read_b128 v[76:79], v139 offset:19456
	ds_read_b128 v[80:83], v139 offset:20480
	ds_read_b128 v[84:87], v139 offset:21504
	ds_read_b128 v[88:91], v139 offset:22528
	ds_read_b128 v[92:95], v139 offset:23552
	global_load_lds_dwordx4 v128, s[38:39]
	s_add_i32 m0, s28, 0x2000
	s_add_u32 s28, s38, 0x40000
	s_addc_u32 s29, s39, 0
	s_add_i32 s62, s56, s43
	global_load_lds_dwordx4 v130, s[38:39]
	s_mov_b32 m0, s62
	s_nop 0
	global_load_lds_dwordx4 v128, s[28:29]
	s_add_i32 m0, s62, 0x2000
	s_nop 0
	global_load_lds_dwordx4 v130, s[28:29]
	s_mov_b32 m0, s45
	s_nop 0
	global_load_lds_dwordx4 v128, s[40:41]
	s_mov_b32 m0, s46
	s_nop 0
	global_load_lds_dwordx4 v130, s[40:41]
	s_waitcnt vmcnt(8)
	s_waitcnt lgkmcnt(0)
	s_barrier
	s_setprio 1
	s_waitcnt lgkmcnt(0)
	v_mfma_scale_f32_16x16x128_f8f6f4 v[60:63], v[142:149], v[64:71], v[60:63], v140, v140 op_sel_hi:[0,0,0]
	v_mfma_scale_f32_16x16x128_f8f6f4 v[56:59], v[150:157], v[64:71], v[56:59], v140, v140 op_sel_hi:[0,0,0]
	v_mfma_scale_f32_16x16x128_f8f6f4 v[48:51], v[142:149], v[72:79], v[48:51], v140, v140 op_sel_hi:[0,0,0]
	v_mfma_scale_f32_16x16x128_f8f6f4 v[194:197], v[150:157], v[72:79], v[40:43], v140, v140 op_sel_hi:[0,0,0]
	v_mfma_scale_f32_16x16x128_f8f6f4 v[198:201], v[142:149], v[80:87], v[32:35], v140, v140 op_sel_hi:[0,0,0]
	v_mfma_scale_f32_16x16x128_f8f6f4 v[202:205], v[150:157], v[80:87], v[24:27], v140, v140 op_sel_hi:[0,0,0]
	v_mfma_scale_f32_16x16x128_f8f6f4 v[218:221], v[142:149], v[88:95], v[16:19], v140, v140 op_sel_hi:[0,0,0]
	v_mfma_scale_f32_16x16x128_f8f6f4 v[222:225], v[150:157], v[88:95], v[8:11], v140, v140 op_sel_hi:[0,0,0]
	s_setprio 0
	s_setprio 1
	v_mfma_scale_f32_16x16x128_f8f6f4 v[52:55], v[158:165], v[64:71], v[52:55], v140, v140 op_sel_hi:[0,0,0]
	v_mfma_scale_f32_16x16x128_f8f6f4 v[226:229], v[166:173], v[64:71], v[44:47], v140, v140 op_sel_hi:[0,0,0]
	v_mfma_scale_f32_16x16x128_f8f6f4 v[230:233], v[158:165], v[72:79], v[36:39], v140, v140 op_sel_hi:[0,0,0]
	v_mfma_scale_f32_16x16x128_f8f6f4 v[234:237], v[166:173], v[72:79], v[28:31], v140, v140 op_sel_hi:[0,0,0]
	v_mfma_scale_f32_16x16x128_f8f6f4 v[238:241], v[158:165], v[80:87], v[20:23], v140, v140 op_sel_hi:[0,0,0]
	v_mfma_scale_f32_16x16x128_f8f6f4 v[242:245], v[166:173], v[80:87], v[12:15], v140, v140 op_sel_hi:[0,0,0]
	v_mfma_scale_f32_16x16x128_f8f6f4 v[246:249], v[158:165], v[88:95], v[4:7], v140, v140 op_sel_hi:[0,0,0]
	v_mfma_scale_f32_16x16x128_f8f6f4 v[250:253], v[166:173], v[88:95], v[0:3], v140, v140 op_sel_hi:[0,0,0]
	s_setprio 0
	s_barrier
; #define PG8_WAIT_V(n) asm volatile("s_waitcnt vmcnt(" #n ")" ::: "memory")
; #define PG8_WAIT_L(n) asm volatile("s_waitcnt lgkmcnt(" #n ")" ::: "memory")
; #define PG8_BAR __builtin_amdgcn_s_barrier()
; #define PG8_SCHED __builtin_amdgcn_sched_barrier(0)
;     ...
;             PG8_LDB(B0, 1, 0); PG8_LDB(B1, 1, 1); PG8_SCHED; PG8_LDA(At, 1, 0); PG8_STAGE(PG8_SA(0, 1), a2 + hstepA, voffA);
;             PG8_WAIT_V(8); PG8_WAIT_L(0); PG8_BAR; PG8_MMA(0, 0, At, B0); PG8_MMA(0, 1, At, B1); PG8_BAR; PG8_SCHED;
;             if constexpr (!HALFU) PG8_LDA(At, 1, 1); PG8_STAGE(PG8_SB(1, 0), b3, voffB); PG8_STAGE(PG8_SB(1, 1), b3 + hstep, voffB); PG8_STAGE(PG8_SA(1, 0), a3, voffA);
;             PG8_WAIT_V(8); PG8_WAIT_L(0); PG8_BAR; if constexpr (!HALFU) { PG8_MMA(1, 0, At, B0); PG8_MMA(1, 1, At, B1); } PG8_BAR; PG8_SCHED;
	s_add_i32 s62, 0, 0x18000
	s_add_i32 s63, 0, 0x1c000
	s_nop 0
	v_add_u32_e32 v12, s62, v136
	v_add_u32_e32 v16, s63, v136
	ds_read_b128 v[0:3], v12
	ds_read_b128 v[4:7], v12 offset:1024
	ds_read_b128 v[8:11], v12 offset:2048
	ds_read_b128 v[12:15], v12 offset:3072
	ds_read_b128 v[142:145], v16
	ds_read_b128 v[146:149], v16 offset:1024
	ds_read_b128 v[150:153], v16 offset:2048
	ds_read_b128 v[154:157], v16 offset:3072
	s_add_u32 s28, s40, 0x40000
	s_addc_u32 s29, s41, 0
	s_mov_b32 m0, s47
	ds_read_b128 v[16:19], v139 offset:32768
	ds_read_b128 v[20:23], v139 offset:33792
	ds_read_b128 v[24:27], v139 offset:34816
	ds_read_b128 v[28:31], v139 offset:35840
	ds_read_b128 v[32:35], v139 offset:36864
	ds_read_b128 v[36:39], v139 offset:37888
	ds_read_b128 v[40:43], v139 offset:38912
	ds_read_b128 v[44:47], v139 offset:39936
	global_load_lds_dwordx4 v128, s[28:29]
	s_mov_b32 m0, s48
	s_nop 0
	global_load_lds_dwordx4 v130, s[28:29]
	s_waitcnt vmcnt(8)
	s_waitcnt lgkmcnt(0)
	s_barrier
	s_setprio 1
	s_waitcnt lgkmcnt(0)
	v_mfma_scale_f32_16x16x128_f8f6f4 v[124:127], v[0:7], v[16:23], v[124:127], v140, v140 op_sel_hi:[0,0,0]
	v_mfma_scale_f32_16x16x128_f8f6f4 v[120:123], v[8:15], v[16:23], v[120:123], v140, v140 op_sel_hi:[0,0,0]
	v_mfma_scale_f32_16x16x128_f8f6f4 v[108:111], v[0:7], v[24:31], v[108:111], v140, v140 op_sel_hi:[0,0,0]
	v_mfma_scale_f32_16x16x128_f8f6f4 v[104:107], v[8:15], v[24:31], v[104:107], v140, v140 op_sel_hi:[0,0,0]
	v_mfma_scale_f32_16x16x128_f8f6f4 v[96:99], v[0:7], v[32:39], v[96:99], v140, v140 op_sel_hi:[0,0,0]
	v_mfma_scale_f32_16x16x128_f8f6f4 v[88:91], v[8:15], v[32:39], v[206:209], v140, v140 op_sel_hi:[0,0,0]
	v_mfma_scale_f32_16x16x128_f8f6f4 v[80:83], v[0:7], v[40:47], v[210:213], v140, v140 op_sel_hi:[0,0,0]
	v_mfma_scale_f32_16x16x128_f8f6f4 v[72:75], v[8:15], v[40:47], v[214:217], v140, v140 op_sel_hi:[0,0,0]
	s_setprio 0
	s_setprio 1
	v_mfma_scale_f32_16x16x128_f8f6f4 v[116:119], v[142:149], v[16:23], v[116:119], v140, v140 op_sel_hi:[0,0,0]
	v_mfma_scale_f32_16x16x128_f8f6f4 v[112:115], v[150:157], v[16:23], v[112:115], v140, v140 op_sel_hi:[0,0,0]
	v_mfma_scale_f32_16x16x128_f8f6f4 v[100:103], v[142:149], v[24:31], v[100:103], v140, v140 op_sel_hi:[0,0,0]
	v_mfma_scale_f32_16x16x128_f8f6f4 v[92:95], v[150:157], v[24:31], v[174:177], v140, v140 op_sel_hi:[0,0,0]
	v_mfma_scale_f32_16x16x128_f8f6f4 v[84:87], v[142:149], v[32:39], v[178:181], v140, v140 op_sel_hi:[0,0,0]
	v_mfma_scale_f32_16x16x128_f8f6f4 v[76:79], v[150:157], v[32:39], v[182:185], v140, v140 op_sel_hi:[0,0,0]
	v_mfma_scale_f32_16x16x128_f8f6f4 v[68:71], v[142:149], v[40:47], v[186:189], v140, v140 op_sel_hi:[0,0,0]
	v_mfma_scale_f32_16x16x128_f8f6f4 v[64:67], v[150:157], v[40:47], v[190:193], v140, v140 op_sel_hi:[0,0,0]
	s_setprio 0
	s_barrier
	s_add_u32 s28, s38, 0x80
	s_addc_u32 s29, s39, 0
	s_add_i32 s40, s62, s43
	s_mov_b32 m0, s40
	ds_read_b128 v[158:161], v139 offset:49152
	ds_read_b128 v[162:165], v139 offset:50176
	ds_read_b128 v[166:169], v139 offset:51200
	ds_read_b128 v[170:173], v139 offset:52224
	ds_read_b128 v[174:177], v139 offset:53248
	ds_read_b128 v[178:181], v139 offset:54272
	ds_read_b128 v[182:185], v139 offset:55296
	ds_read_b128 v[186:189], v139 offset:56320
	global_load_lds_dwordx4 v128, s[28:29]
	s_add_i32 m0, s40, 0x2000
	v_lshl_add_u64 v[16:17], s[28:29], 0, v[130:131]
	s_add_u32 s28, s38, 0x40080
	s_addc_u32 s29, s39, 0
	s_add_i32 s38, s63, s43
	global_load_lds_dwordx4 v[16:17], off
	s_mov_b32 m0, s38
	s_nop 0
	global_load_lds_dwordx4 v128, s[28:29]
	s_add_i32 m0, s38, 0x2000
	s_nop 0
	global_load_lds_dwordx4 v130, s[28:29]
	s_mov_b32 m0, s53
	s_nop 0
	global_load_lds_dwordx4 v128, s[36:37]
	s_mov_b32 m0, s54
	s_nop 0
	global_load_lds_dwordx4 v130, s[36:37]
	s_waitcnt vmcnt(8)
	s_waitcnt lgkmcnt(0)
	s_barrier
	s_setprio 1
	s_waitcnt lgkmcnt(0)
	v_mfma_scale_f32_16x16x128_f8f6f4 v[60:63], v[0:7], v[158:165], v[60:63], v140, v140 op_sel_hi:[0,0,0]
	v_mfma_scale_f32_16x16x128_f8f6f4 v[56:59], v[8:15], v[158:165], v[56:59], v140, v140 op_sel_hi:[0,0,0]
	v_mfma_scale_f32_16x16x128_f8f6f4 v[48:51], v[0:7], v[166:173], v[48:51], v140, v140 op_sel_hi:[0,0,0]
	v_mfma_scale_f32_16x16x128_f8f6f4 v[40:43], v[8:15], v[166:173], v[194:197], v140, v140 op_sel_hi:[0,0,0]
	v_mfma_scale_f32_16x16x128_f8f6f4 v[32:35], v[0:7], v[174:181], v[198:201], v140, v140 op_sel_hi:[0,0,0]
	v_mfma_scale_f32_16x16x128_f8f6f4 v[24:27], v[8:15], v[174:181], v[202:205], v140, v140 op_sel_hi:[0,0,0]
	v_mfma_scale_f32_16x16x128_f8f6f4 v[16:19], v[0:7], v[182:189], v[218:221], v140, v140 op_sel_hi:[0,0,0]
	v_mfma_scale_f32_16x16x128_f8f6f4 v[8:11], v[8:15], v[182:189], v[222:225], v140, v140 op_sel_hi:[0,0,0]
	s_setprio 0
	s_setprio 1
	v_mfma_scale_f32_16x16x128_f8f6f4 v[52:55], v[142:149], v[158:165], v[52:55], v140, v140 op_sel_hi:[0,0,0]
	v_mfma_scale_f32_16x16x128_f8f6f4 v[44:47], v[150:157], v[158:165], v[226:229], v140, v140 op_sel_hi:[0,0,0]
	v_mfma_scale_f32_16x16x128_f8f6f4 v[36:39], v[142:149], v[166:173], v[230:233], v140, v140 op_sel_hi:[0,0,0]
	v_mfma_scale_f32_16x16x128_f8f6f4 v[28:31], v[150:157], v[166:173], v[234:237], v140, v140 op_sel_hi:[0,0,0]
	v_mfma_scale_f32_16x16x128_f8f6f4 v[20:23], v[142:149], v[174:181], v[238:241], v140, v140 op_sel_hi:[0,0,0]
	v_mfma_scale_f32_16x16x128_f8f6f4 v[12:15], v[150:157], v[174:181], v[242:245], v140, v140 op_sel_hi:[0,0,0]
	v_mfma_scale_f32_16x16x128_f8f6f4 v[4:7], v[142:149], v[182:189], v[246:249], v140, v140 op_sel_hi:[0,0,0]
	v_mfma_scale_f32_16x16x128_f8f6f4 v[0:3], v[150:157], v[182:189], v[250:253], v140, v140 op_sel_hi:[0,0,0]
	s_setprio 0
	s_barrier
	s_add_i32 s61, s61, 2
	s_add_u32 s59, s59, 0x100
	s_addc_u32 s60, s60, 0
	s_cmp_gt_u32 s61, 13
	s_mov_b64 s[28:29], s[30:31]
	s_cbranch_scc0 .LBB0_542
	s_and_b64 vcc, exec, s[6:7]
	s_cbranch_vccz .LBB0_545
	s_barrier

; #define PG8_WAIT_V(n) asm volatile("s_waitcnt vmcnt(" #n ")" ::: "memory")
; #define PG8_BAR __builtin_amdgcn_s_barrier()
;     ...
;     if constexpr (SP2) {
;         PG8_STAGE(PG8_SB(0, 0), cB, voffB); PG8_STAGE(PG8_SB(0, 1), cB + hstep, voffB); PG8_STAGE(PG8_SA(0, 0), cA, voffA); PG8_STAGE(PG8_SA(0, 1), cA + hstepA, voffA);
;         if (wr == 1) PG8_BAR;
;         PG8_WAIT_V(2); PG8_BAR;
;         PG8_STAGE(PG8_SB(1, 0), cB + kstep, voffB); PG8_STAGE(PG8_SA(1, 0), cA + kstep, voffA); PG8_STAGE(PG8_SB(1, 1), cB + hstep + kstep, voffB);
;         PG8_WAIT_V(6); PG8_BAR;
.LBB0_664:
	s_lshl_b32 s6, s6, 5
	s_and_b32 s42, s6, 0x60
	s_ashr_i32 s40, s88, 31
	s_lshl_b32 s41, s7, 6
	s_lshl_b32 s8, s7, 13
	s_lshl_b32 s9, s42, 7
	s_add_u32 s6, s20, 0x80
	s_addc_u32 s7, s21, 0
	s_add_i32 m0, s17, 0x18000
	s_waitcnt vmcnt(2)
	s_barrier
	global_load_lds_dwordx4 v128, s[6:7]
	s_add_i32 m0, s17, 0x1a000
	v_lshl_add_u64 v[2:3], s[6:7], 0, v[130:131]
	s_add_u32 s6, s18, 0x80
	s_addc_u32 s7, s19, 0
	s_add_i32 s43, s17, 0x8000
	global_load_lds_dwordx4 v[2:3], off
	s_mov_b32 m0, s43
	s_add_i32 s44, s17, 0xa000
	global_load_lds_dwordx4 v134, s[6:7]
	v_lshl_add_u64 v[2:3], s[6:7], 0, v[132:133]
	s_add_u32 s6, s20, 0x100080
	s_mov_b32 m0, s44
	s_addc_u32 s7, s21, 0
	global_load_lds_dwordx4 v[2:3], off
	s_add_i32 m0, s17, 0x1c000
	global_load_lds_dwordx4 v128, s[6:7]
	s_add_i32 m0, s17, 0x1e000
	s_sext_i32_i16 s48, s4
	global_load_lds_dwordx4 v130, s[6:7]
	v_and_b32_e32 v1, 48, v0
	v_lshlrev_b32_e32 v2, 6, v0
	s_movk_i32 s4, 0x3c0
	v_lshlrev_b32_e32 v0, 2, v0
	v_and_or_b32 v1, v2, s4, v1
	v_and_b32_e32 v0, 32, v0
	s_waitcnt vmcnt(6)
	s_cmpk_lt_u32 s5, 0x100
	v_bitop3_b32 v2, v1, s8, v0 bitop3:0xde
	v_bitop3_b32 v140, s9, v1, v0 bitop3:0xf6
	s_cselect_b64 s[6:7], -1, 0
	s_add_i32 s45, 0, 0x10000
	s_add_i32 s46, 0, 0x14000
	v_mov_b64_e32 v[136:137], 0x1580
	v_mov_b64_e32 v[138:139], 0x157f
	v_add_u32_e32 v141, s45, v140
	v_add_u32_e32 v142, s46, v140
	v_add_u32_e32 v143, 0, v2
	s_movk_i32 s47, 0x5600
	s_barrier
	s_branch .LBB0_667

; #define PG8_WAIT_V(n) asm volatile("s_waitcnt vmcnt(" #n ")" ::: "memory")
; #define PG8_WAIT_L(n) asm volatile("s_waitcnt lgkmcnt(" #n ")" ::: "memory")
; #define PG8_BAR __builtin_amdgcn_s_barrier()
; #define PG8_SCHED __builtin_amdgcn_sched_barrier(0)
;     ...
;             PG8_LDB(B0, 0, 0); PG8_LDB(B1, 0, 1); PG8_SCHED; PG8_LDA(At, 0, 0); PG8_STAGE(PG8_SA(1, 1), a1 + hstepA, voffA);
;             PG8_WAIT_V(8); PG8_WAIT_L(0); PG8_BAR; PG8_MMA(0, 0, At, B0); PG8_MMA(0, 1, At, B1); PG8_BAR; PG8_SCHED;
;             if constexpr (!HALFU) PG8_LDA(At, 0, 1); PG8_STAGE(PG8_SB(0, 0), b2, voffB); PG8_STAGE(PG8_SB(0, 1), b2 + hstep, voffB); PG8_STAGE(PG8_SA(0, 0), a2, voffA);
;             PG8_WAIT_V(8); PG8_WAIT_L(0); PG8_BAR; if constexpr (!HALFU) { PG8_MMA(1, 0, At, B0); PG8_MMA(1, 1, At, B1); } PG8_BAR; PG8_SCHED;
.LBB0_670:
	ds_read_b128 v[144:147], v141
	ds_read_b128 v[148:151], v141 offset:1024
	ds_read_b128 v[152:155], v141 offset:2048
	ds_read_b128 v[156:159], v141 offset:3072
	ds_read_b128 v[160:163], v142
	ds_read_b128 v[164:167], v142 offset:1024
	ds_read_b128 v[168:171], v142 offset:2048
	ds_read_b128 v[172:175], v142 offset:3072
	s_add_u32 s20, s18, 0x100
	s_addc_u32 s21, s19, 0
	s_cmp_eq_u32 s53, 60
	s_cselect_b32 s26, s49, s20
	s_cselect_b32 s27, s11, s21
	s_cselect_b32 s24, s50, s51
	s_cselect_b32 s25, s9, s52
	s_add_u32 s22, s26, 0x80
	s_addc_u32 s23, s27, 0
	s_add_u32 s18, s18, 0x100080
	s_addc_u32 s19, s19, 0
	s_add_i32 m0, s17, 0xc000
	ds_read_b128 v[176:179], v143
	ds_read_b128 v[180:183], v143 offset:1024
	ds_read_b128 v[184:187], v143 offset:2048
	ds_read_b128 v[188:191], v143 offset:3072
	ds_read_b128 v[192:195], v143 offset:4096
	ds_read_b128 v[196:199], v143 offset:5120
	ds_read_b128 v[200:203], v143 offset:6144
	ds_read_b128 v[204:207], v143 offset:7168
	global_load_lds_dwordx4 v134, s[18:19]
	s_add_i32 m0, s17, 0xe000
	s_nop 0
	global_load_lds_dwordx4 v132, s[18:19]
	s_waitcnt vmcnt(8)
	s_waitcnt lgkmcnt(0)
	s_barrier
	s_setprio 1
	s_waitcnt lgkmcnt(0)
	v_mfma_f32_16x16x32_bf16 v[124:127], v[144:147], v[176:179], v[124:127]
	v_mfma_f32_16x16x32_bf16 v[120:123], v[152:155], v[176:179], v[120:123]
	v_mfma_f32_16x16x32_bf16 v[108:111], v[144:147], v[184:187], v[108:111]
	v_mfma_f32_16x16x32_bf16 v[104:107], v[152:155], v[184:187], v[104:107]
	v_mfma_f32_16x16x32_bf16 v[92:95], v[144:147], v[192:195], v[92:95]
	v_mfma_f32_16x16x32_bf16 v[88:91], v[152:155], v[192:195], v[88:91]
	v_mfma_f32_16x16x32_bf16 v[76:79], v[144:147], v[200:203], v[76:79]
	v_mfma_f32_16x16x32_bf16 v[72:75], v[152:155], v[200:203], v[72:75]
	v_mfma_f32_16x16x32_bf16 v[124:127], v[148:151], v[180:183], v[124:127]
	v_mfma_f32_16x16x32_bf16 v[120:123], v[156:159], v[180:183], v[120:123]
	v_mfma_f32_16x16x32_bf16 v[108:111], v[148:151], v[188:191], v[108:111]
	v_mfma_f32_16x16x32_bf16 v[104:107], v[156:159], v[188:191], v[104:107]
	v_mfma_f32_16x16x32_bf16 v[92:95], v[148:151], v[196:199], v[92:95]
	v_mfma_f32_16x16x32_bf16 v[88:91], v[156:159], v[196:199], v[88:91]
	v_mfma_f32_16x16x32_bf16 v[76:79], v[148:151], v[204:207], v[76:79]
	v_mfma_f32_16x16x32_bf16 v[72:75], v[156:159], v[204:207], v[72:75]
	s_setprio 0
	s_setprio 1
	v_mfma_f32_16x16x32_bf16 v[116:119], v[160:163], v[176:179], v[116:119]
	v_mfma_f32_16x16x32_bf16 v[112:115], v[168:171], v[176:179], v[112:115]
	v_mfma_f32_16x16x32_bf16 v[100:103], v[160:163], v[184:187], v[100:103]
	v_mfma_f32_16x16x32_bf16 v[96:99], v[168:171], v[184:187], v[96:99]
	v_mfma_f32_16x16x32_bf16 v[84:87], v[160:163], v[192:195], v[84:87]
	v_mfma_f32_16x16x32_bf16 v[80:83], v[168:171], v[192:195], v[80:83]
	v_mfma_f32_16x16x32_bf16 v[68:71], v[160:163], v[200:203], v[68:71]
	v_mfma_f32_16x16x32_bf16 v[64:67], v[168:171], v[200:203], v[64:67]
	v_mfma_f32_16x16x32_bf16 v[116:119], v[164:167], v[180:183], v[116:119]
	v_mfma_f32_16x16x32_bf16 v[112:115], v[172:175], v[180:183], v[112:115]
	v_mfma_f32_16x16x32_bf16 v[100:103], v[164:167], v[188:191], v[100:103]
	v_mfma_f32_16x16x32_bf16 v[96:99], v[172:175], v[188:191], v[96:99]
	v_mfma_f32_16x16x32_bf16 v[84:87], v[164:167], v[196:199], v[84:87]
	v_mfma_f32_16x16x32_bf16 v[80:83], v[172:175], v[196:199], v[80:83]
	v_mfma_f32_16x16x32_bf16 v[68:71], v[164:167], v[204:207], v[68:71]
	v_mfma_f32_16x16x32_bf16 v[64:67], v[172:175], v[204:207], v[64:67]
	s_setprio 0
	s_barrier
	s_add_i32 s18, s45, s30
	s_mov_b32 m0, s18
	ds_read_b128 v[176:179], v143 offset:16384
	ds_read_b128 v[180:183], v143 offset:17408
	ds_read_b128 v[184:187], v143 offset:18432
	ds_read_b128 v[188:191], v143 offset:19456
	ds_read_b128 v[192:195], v143 offset:20480
	ds_read_b128 v[196:199], v143 offset:21504
	ds_read_b128 v[200:203], v143 offset:22528
	ds_read_b128 v[204:207], v143 offset:23552
	global_load_lds_dwordx4 v128, s[24:25]
	s_add_i32 m0, s18, 0x2000
	s_add_u32 s18, s24, 0x100000
	s_addc_u32 s19, s25, 0
	s_add_i32 s54, s46, s30
	global_load_lds_dwordx4 v130, s[24:25]
	s_mov_b32 m0, s54
	s_nop 0
	global_load_lds_dwordx4 v128, s[18:19]
	s_add_i32 m0, s54, 0x2000
	s_nop 0
	global_load_lds_dwordx4 v130, s[18:19]
	s_mov_b32 m0, s17
	s_nop 0
	global_load_lds_dwordx4 v134, s[26:27]
	s_mov_b32 m0, s36
	s_nop 0
	global_load_lds_dwordx4 v132, s[26:27]
	s_waitcnt vmcnt(8)
	s_waitcnt lgkmcnt(0)
	s_barrier
	s_setprio 1
	s_waitcnt lgkmcnt(0)
	v_mfma_f32_16x16x32_bf16 v[60:63], v[144:147], v[176:179], v[60:63]
	v_mfma_f32_16x16x32_bf16 v[56:59], v[152:155], v[176:179], v[56:59]
	v_mfma_f32_16x16x32_bf16 v[44:47], v[144:147], v[184:187], v[44:47]
	v_mfma_f32_16x16x32_bf16 v[40:43], v[152:155], v[184:187], v[40:43]
	v_mfma_f32_16x16x32_bf16 v[28:31], v[144:147], v[192:195], v[28:31]
	v_mfma_f32_16x16x32_bf16 v[24:27], v[152:155], v[192:195], v[24:27]
	v_mfma_f32_16x16x32_bf16 v[12:15], v[144:147], v[200:203], v[12:15]
	v_mfma_f32_16x16x32_bf16 v[8:11], v[152:155], v[200:203], v[8:11]
	v_mfma_f32_16x16x32_bf16 v[60:63], v[148:151], v[180:183], v[60:63]
	v_mfma_f32_16x16x32_bf16 v[56:59], v[156:159], v[180:183], v[56:59]
	v_mfma_f32_16x16x32_bf16 v[44:47], v[148:151], v[188:191], v[44:47]
	v_mfma_f32_16x16x32_bf16 v[40:43], v[156:159], v[188:191], v[40:43]
	v_mfma_f32_16x16x32_bf16 v[28:31], v[148:151], v[196:199], v[28:31]
	v_mfma_f32_16x16x32_bf16 v[24:27], v[156:159], v[196:199], v[24:27]
	v_mfma_f32_16x16x32_bf16 v[12:15], v[148:151], v[204:207], v[12:15]
	v_mfma_f32_16x16x32_bf16 v[8:11], v[156:159], v[204:207], v[8:11]
	s_setprio 0
	s_setprio 1
	v_mfma_f32_16x16x32_bf16 v[52:55], v[160:163], v[176:179], v[52:55]
	v_mfma_f32_16x16x32_bf16 v[48:51], v[168:171], v[176:179], v[48:51]
	v_mfma_f32_16x16x32_bf16 v[36:39], v[160:163], v[184:187], v[36:39]
	v_mfma_f32_16x16x32_bf16 v[32:35], v[168:171], v[184:187], v[32:35]
	v_mfma_f32_16x16x32_bf16 v[20:23], v[160:163], v[192:195], v[20:23]
	v_mfma_f32_16x16x32_bf16 v[16:19], v[168:171], v[192:195], v[16:19]
	v_mfma_f32_16x16x32_bf16 v[4:7], v[160:163], v[200:203], v[4:7]
	v_mfma_f32_16x16x32_bf16 v[0:3], v[168:171], v[200:203], v[0:3]
	v_mfma_f32_16x16x32_bf16 v[52:55], v[164:167], v[180:183], v[52:55]
	v_mfma_f32_16x16x32_bf16 v[48:51], v[172:175], v[180:183], v[48:51]
	v_mfma_f32_16x16x32_bf16 v[36:39], v[164:167], v[188:191], v[36:39]
	v_mfma_f32_16x16x32_bf16 v[32:35], v[172:175], v[188:191], v[32:35]
	v_mfma_f32_16x16x32_bf16 v[20:23], v[164:167], v[196:199], v[20:23]
	v_mfma_f32_16x16x32_bf16 v[16:19], v[172:175], v[196:199], v[16:19]
	v_mfma_f32_16x16x32_bf16 v[4:7], v[164:167], v[204:207], v[4:7]
	v_mfma_f32_16x16x32_bf16 v[0:3], v[172:175], v[204:207], v[0:3]
	s_setprio 0
	s_barrier
; #define PG8_WAIT_V(n) asm volatile("s_waitcnt vmcnt(" #n ")" ::: "memory")
; #define PG8_WAIT_L(n) asm volatile("s_waitcnt lgkmcnt(" #n ")" ::: "memory")
; #define PG8_BAR __builtin_amdgcn_s_barrier()
; #define PG8_SCHED __builtin_amdgcn_sched_barrier(0)
;     ...
;             PG8_LDB(B0, 1, 0); PG8_LDB(B1, 1, 1); PG8_SCHED; PG8_LDA(At, 1, 0); PG8_STAGE(PG8_SA(0, 1), a2 + hstepA, voffA);
;             PG8_WAIT_V(8); PG8_WAIT_L(0); PG8_BAR; PG8_MMA(0, 0, At, B0); PG8_MMA(0, 1, At, B1); PG8_BAR; PG8_SCHED;
;             if constexpr (!HALFU) PG8_LDA(At, 1, 1); PG8_STAGE(PG8_SB(1, 0), b3, voffB); PG8_STAGE(PG8_SB(1, 1), b3 + hstep, voffB); PG8_STAGE(PG8_SA(1, 0), a3, voffA);
;             PG8_WAIT_V(8); PG8_WAIT_L(0); PG8_BAR; if constexpr (!HALFU) { PG8_MMA(1, 0, At, B0); PG8_MMA(1, 1, At, B1); } PG8_BAR; PG8_SCHED;
	s_add_i32 s54, 0, 0x18000
	s_add_i32 s55, 0, 0x1c000
	v_add_u32_e32 v156, s54, v140
	v_add_u32_e32 v172, s55, v140
	ds_read_b128 v[144:147], v156
	ds_read_b128 v[148:151], v156 offset:1024
	ds_read_b128 v[152:155], v156 offset:2048
	ds_read_b128 v[156:159], v156 offset:3072
	ds_read_b128 v[160:163], v172
	ds_read_b128 v[164:167], v172 offset:1024
	ds_read_b128 v[168:171], v172 offset:2048
	ds_read_b128 v[172:175], v172 offset:3072
	s_add_u32 s18, s26, 0x100000
	s_addc_u32 s19, s27, 0
	s_mov_b32 m0, s37
	ds_read_b128 v[176:179], v143 offset:32768
	ds_read_b128 v[180:183], v143 offset:33792
	ds_read_b128 v[184:187], v143 offset:34816
	ds_read_b128 v[188:191], v143 offset:35840
	ds_read_b128 v[192:195], v143 offset:36864
	ds_read_b128 v[196:199], v143 offset:37888
	ds_read_b128 v[200:203], v143 offset:38912
	ds_read_b128 v[204:207], v143 offset:39936
	global_load_lds_dwordx4 v134, s[18:19]
	s_mov_b32 m0, s38
	s_nop 0
	global_load_lds_dwordx4 v132, s[18:19]
	s_waitcnt vmcnt(8)
	s_waitcnt lgkmcnt(0)
	s_barrier
	s_setprio 1
	s_waitcnt lgkmcnt(0)
	v_mfma_f32_16x16x32_bf16 v[124:127], v[144:147], v[176:179], v[124:127]
	v_mfma_f32_16x16x32_bf16 v[120:123], v[152:155], v[176:179], v[120:123]
	v_mfma_f32_16x16x32_bf16 v[108:111], v[144:147], v[184:187], v[108:111]
	v_mfma_f32_16x16x32_bf16 v[104:107], v[152:155], v[184:187], v[104:107]
	v_mfma_f32_16x16x32_bf16 v[92:95], v[144:147], v[192:195], v[92:95]
	v_mfma_f32_16x16x32_bf16 v[88:91], v[152:155], v[192:195], v[88:91]
	v_mfma_f32_16x16x32_bf16 v[76:79], v[144:147], v[200:203], v[76:79]
	v_mfma_f32_16x16x32_bf16 v[72:75], v[152:155], v[200:203], v[72:75]
	v_mfma_f32_16x16x32_bf16 v[124:127], v[148:151], v[180:183], v[124:127]
	v_mfma_f32_16x16x32_bf16 v[120:123], v[156:159], v[180:183], v[120:123]
	v_mfma_f32_16x16x32_bf16 v[108:111], v[148:151], v[188:191], v[108:111]
	v_mfma_f32_16x16x32_bf16 v[104:107], v[156:159], v[188:191], v[104:107]
	v_mfma_f32_16x16x32_bf16 v[92:95], v[148:151], v[196:199], v[92:95]
	v_mfma_f32_16x16x32_bf16 v[88:91], v[156:159], v[196:199], v[88:91]
	v_mfma_f32_16x16x32_bf16 v[76:79], v[148:151], v[204:207], v[76:79]
	v_mfma_f32_16x16x32_bf16 v[72:75], v[156:159], v[204:207], v[72:75]
	s_setprio 0
	s_setprio 1
	v_mfma_f32_16x16x32_bf16 v[116:119], v[160:163], v[176:179], v[116:119]
	v_mfma_f32_16x16x32_bf16 v[112:115], v[168:171], v[176:179], v[112:115]
	v_mfma_f32_16x16x32_bf16 v[100:103], v[160:163], v[184:187], v[100:103]
	v_mfma_f32_16x16x32_bf16 v[96:99], v[168:171], v[184:187], v[96:99]
	v_mfma_f32_16x16x32_bf16 v[84:87], v[160:163], v[192:195], v[84:87]
	v_mfma_f32_16x16x32_bf16 v[80:83], v[168:171], v[192:195], v[80:83]
	v_mfma_f32_16x16x32_bf16 v[68:71], v[160:163], v[200:203], v[68:71]
	v_mfma_f32_16x16x32_bf16 v[64:67], v[168:171], v[200:203], v[64:67]
	v_mfma_f32_16x16x32_bf16 v[116:119], v[164:167], v[180:183], v[116:119]
	v_mfma_f32_16x16x32_bf16 v[112:115], v[172:175], v[180:183], v[112:115]
	v_mfma_f32_16x16x32_bf16 v[100:103], v[164:167], v[188:191], v[100:103]
	v_mfma_f32_16x16x32_bf16 v[96:99], v[172:175], v[188:191], v[96:99]
	v_mfma_f32_16x16x32_bf16 v[84:87], v[164:167], v[196:199], v[84:87]
	v_mfma_f32_16x16x32_bf16 v[80:83], v[172:175], v[196:199], v[80:83]
	v_mfma_f32_16x16x32_bf16 v[68:71], v[164:167], v[204:207], v[68:71]
	v_mfma_f32_16x16x32_bf16 v[64:67], v[172:175], v[204:207], v[64:67]
	s_setprio 0
	s_barrier
	s_add_u32 s18, s24, 0x80
	s_addc_u32 s19, s25, 0
	s_add_i32 s26, s54, s30
	s_mov_b32 m0, s26
	ds_read_b128 v[176:179], v143 offset:49152
	ds_read_b128 v[180:183], v143 offset:50176
	ds_read_b128 v[184:187], v143 offset:51200
	ds_read_b128 v[188:191], v143 offset:52224
	ds_read_b128 v[192:195], v143 offset:53248
	ds_read_b128 v[196:199], v143 offset:54272
	ds_read_b128 v[200:203], v143 offset:55296
	ds_read_b128 v[204:207], v143 offset:56320
	global_load_lds_dwordx4 v128, s[18:19]
	s_add_i32 m0, s26, 0x2000
	v_lshl_add_u64 v[208:209], s[18:19], 0, v[130:131]
	s_add_u32 s18, s24, 0x100080
	s_addc_u32 s19, s25, 0
	s_add_i32 s24, s55, s30
	global_load_lds_dwordx4 v[208:209], off
	s_mov_b32 m0, s24
	s_nop 0
	global_load_lds_dwordx4 v128, s[18:19]
	s_add_i32 m0, s24, 0x2000
	s_nop 0
	global_load_lds_dwordx4 v130, s[18:19]
	s_mov_b32 m0, s43
	s_nop 0
	global_load_lds_dwordx4 v134, s[22:23]
	s_mov_b32 m0, s44
	s_nop 0
	global_load_lds_dwordx4 v132, s[22:23]
	s_waitcnt vmcnt(8)
	s_waitcnt lgkmcnt(0)
	s_barrier
	s_setprio 1
	s_waitcnt lgkmcnt(0)
	v_mfma_f32_16x16x32_bf16 v[60:63], v[144:147], v[176:179], v[60:63]
	v_mfma_f32_16x16x32_bf16 v[56:59], v[152:155], v[176:179], v[56:59]
	v_mfma_f32_16x16x32_bf16 v[44:47], v[144:147], v[184:187], v[44:47]
	v_mfma_f32_16x16x32_bf16 v[40:43], v[152:155], v[184:187], v[40:43]
	v_mfma_f32_16x16x32_bf16 v[28:31], v[144:147], v[192:195], v[28:31]
	v_mfma_f32_16x16x32_bf16 v[24:27], v[152:155], v[192:195], v[24:27]
	v_mfma_f32_16x16x32_bf16 v[12:15], v[144:147], v[200:203], v[12:15]
	v_mfma_f32_16x16x32_bf16 v[8:11], v[152:155], v[200:203], v[8:11]
	v_mfma_f32_16x16x32_bf16 v[60:63], v[148:151], v[180:183], v[60:63]
	v_mfma_f32_16x16x32_bf16 v[56:59], v[156:159], v[180:183], v[56:59]
	v_mfma_f32_16x16x32_bf16 v[44:47], v[148:151], v[188:191], v[44:47]
	v_mfma_f32_16x16x32_bf16 v[40:43], v[156:159], v[188:191], v[40:43]
	v_mfma_f32_16x16x32_bf16 v[28:31], v[148:151], v[196:199], v[28:31]
	v_mfma_f32_16x16x32_bf16 v[24:27], v[156:159], v[196:199], v[24:27]
	v_mfma_f32_16x16x32_bf16 v[12:15], v[148:151], v[204:207], v[12:15]
	v_mfma_f32_16x16x32_bf16 v[8:11], v[156:159], v[204:207], v[8:11]
	s_setprio 0
	s_setprio 1
	v_mfma_f32_16x16x32_bf16 v[52:55], v[160:163], v[176:179], v[52:55]
	v_mfma_f32_16x16x32_bf16 v[48:51], v[168:171], v[176:179], v[48:51]
	v_mfma_f32_16x16x32_bf16 v[36:39], v[160:163], v[184:187], v[36:39]
	v_mfma_f32_16x16x32_bf16 v[32:35], v[168:171], v[184:187], v[32:35]
	v_mfma_f32_16x16x32_bf16 v[20:23], v[160:163], v[192:195], v[20:23]
	v_mfma_f32_16x16x32_bf16 v[16:19], v[168:171], v[192:195], v[16:19]
	v_mfma_f32_16x16x32_bf16 v[4:7], v[160:163], v[200:203], v[4:7]
	v_mfma_f32_16x16x32_bf16 v[0:3], v[168:171], v[200:203], v[0:3]
	v_mfma_f32_16x16x32_bf16 v[52:55], v[164:167], v[180:183], v[52:55]
	v_mfma_f32_16x16x32_bf16 v[48:51], v[172:175], v[180:183], v[48:51]
	v_mfma_f32_16x16x32_bf16 v[36:39], v[164:167], v[188:191], v[36:39]
	v_mfma_f32_16x16x32_bf16 v[32:35], v[172:175], v[188:191], v[32:35]
	v_mfma_f32_16x16x32_bf16 v[20:23], v[164:167], v[196:199], v[20:23]
	v_mfma_f32_16x16x32_bf16 v[16:19], v[172:175], v[196:199], v[16:19]
	v_mfma_f32_16x16x32_bf16 v[4:7], v[164:167], v[204:207], v[4:7]
	v_mfma_f32_16x16x32_bf16 v[0:3], v[172:175], v[204:207], v[0:3]
	s_setprio 0
	s_barrier
	s_add_i32 s53, s53, 2
	s_add_u32 s51, s51, 0x100
	s_addc_u32 s52, s52, 0
	s_cmp_gt_u32 s53, 61
	s_mov_b64 s[18:19], s[20:21]
	s_cbranch_scc0 .LBB0_670
	s_and_b64 vcc, exec, s[6:7]
	s_cbranch_vccz .LBB0_673
	s_barrier

; #define PG8_WAIT_V(n) asm volatile("s_waitcnt vmcnt(" #n ")" ::: "memory")
; #define PG8_BAR __builtin_amdgcn_s_barrier()
;     ...
;     if constexpr (SP2) {
;         PG8_STAGE(PG8_SB(0, 0), cB, voffB); PG8_STAGE(PG8_SB(0, 1), cB + hstep, voffB); PG8_STAGE(PG8_SA(0, 0), cA, voffA); PG8_STAGE(PG8_SA(0, 1), cA + hstepA, voffA);
;         if (wr == 1) PG8_BAR;
;         PG8_WAIT_V(2); PG8_BAR;
;         PG8_STAGE(PG8_SB(1, 0), cB + kstep, voffB); PG8_STAGE(PG8_SA(1, 0), cA + kstep, voffA); PG8_STAGE(PG8_SB(1, 1), cB + hstep + kstep, voffB);
;         PG8_WAIT_V(6); PG8_BAR;
.LBB0_779:
	s_and_b32 s6, s6, 3
	s_and_b32 s17, s58, 0xffff
	s_and_b32 s9, s35, 0xffff
	s_ashr_i32 s41, s88, 31
	s_lshl_b32 s42, s5, 6
	s_lshl_b32 s5, s5, 13
	s_lshl_b32 s14, s6, 12
	s_add_u32 s12, s22, 0x80
	s_addc_u32 s13, s23, 0
	s_add_i32 m0, s36, 0x18000
	s_waitcnt vmcnt(2)
	s_barrier
	global_load_lds_dwordx4 v128, s[12:13]
	s_add_i32 m0, s36, 0x1a000
	v_lshl_add_u64 v[2:3], s[12:13], 0, v[130:131]
	s_add_u32 s12, s10, 0x80
	s_addc_u32 s13, s11, 0
	s_add_i32 s43, s36, 0x8000
	global_load_lds_dwordx4 v[2:3], off
	s_mov_b32 m0, s43
	s_add_i32 s44, s36, 0xa000
	global_load_lds_dwordx4 v128, s[12:13]
	v_lshl_add_u64 v[2:3], s[12:13], 0, v[130:131]
	s_add_u32 s12, s22, 0x2b0080
	s_mov_b32 m0, s44
	s_addc_u32 s13, s23, 0
	global_load_lds_dwordx4 v[2:3], off
	s_add_i32 m0, s36, 0x1c000
	global_load_lds_dwordx4 v128, s[12:13]
	s_add_i32 m0, s36, 0x1e000
	s_sext_i32_i8 s51, s7
	global_load_lds_dwordx4 v130, s[12:13]
	v_and_b32_e32 v1, 48, v0
	v_lshlrev_b32_e32 v2, 6, v0
	s_movk_i32 s7, 0x3c0
	v_lshlrev_b32_e32 v0, 2, v0
	v_and_or_b32 v1, v2, s7, v1
	v_and_b32_e32 v0, 32, v0
	s_waitcnt vmcnt(6)
	s_cmpk_lt_u32 s4, 0x100
	v_bitop3_b32 v2, v1, s5, v0 bitop3:0xde
	v_bitop3_b32 v136, s14, v1, v0 bitop3:0xf6
	s_cselect_b64 s[12:13], -1, 0
	s_add_i32 s46, 0, 0x10000
	s_add_i32 s47, 0, 0x14000
	s_mov_b32 s19, 0x20000
	s_brev_b32 s18, 8
	s_mov_b32 s8, s34
	s_lshl_b32 s45, s6, 6
	v_mov_b64_e32 v[132:133], 0x400
	v_mov_b64_e32 v[134:135], 0x3ff
	v_add_u32_e32 v137, s46, v136
	v_add_u32_e32 v138, s47, v136
	v_add_u32_e32 v139, 0, v2
	s_mov_b32 s14, 0x3fb504f3
	s_barrier
	s_branch .LBB0_782

; #define PG8_WAIT_V(n) asm volatile("s_waitcnt vmcnt(" #n ")" ::: "memory")
; #define PG8_WAIT_L(n) asm volatile("s_waitcnt lgkmcnt(" #n ")" ::: "memory")
; #define PG8_BAR __builtin_amdgcn_s_barrier()
; #define PG8_SCHED __builtin_amdgcn_sched_barrier(0)
;     ...
;             PG8_LDB(B0, 0, 0); PG8_LDB(B1, 0, 1); PG8_SCHED; PG8_LDA(At, 0, 0); PG8_STAGE(PG8_SA(1, 1), a1 + hstepA, voffA);
;             PG8_WAIT_V(8); PG8_WAIT_L(0); PG8_BAR; PG8_MMA(0, 0, At, B0); PG8_MMA(0, 1, At, B1); PG8_BAR; PG8_SCHED;
;             if constexpr (!HALFU) PG8_LDA(At, 0, 1); PG8_STAGE(PG8_SB(0, 0), b2, voffB); PG8_STAGE(PG8_SB(0, 1), b2 + hstep, voffB); PG8_STAGE(PG8_SA(0, 0), a2, voffA);
;             PG8_WAIT_V(8); PG8_WAIT_L(0); PG8_BAR; if constexpr (!HALFU) { PG8_MMA(1, 0, At, B0); PG8_MMA(1, 1, At, B1); } PG8_BAR; PG8_SCHED;
.LBB0_793:
	ds_read_b128 v[140:143], v137
	ds_read_b128 v[144:147], v137 offset:1024
	ds_read_b128 v[148:151], v137 offset:2048
	ds_read_b128 v[152:155], v137 offset:3072
	ds_read_b128 v[156:159], v138
	ds_read_b128 v[160:163], v138 offset:1024
	ds_read_b128 v[164:167], v138 offset:2048
	ds_read_b128 v[168:171], v138 offset:3072
	s_add_u32 s22, s10, 0x100
	s_addc_u32 s23, s11, 0
	s_cmpk_eq_i32 s54, 0xa8
	s_cselect_b32 s28, s6, s22
	s_cselect_b32 s29, s7, s23
	s_cselect_b32 s26, s20, s52
	s_cselect_b32 s27, s21, s53
	s_add_u32 s24, s28, 0x80
	s_addc_u32 s25, s29, 0
	s_add_u32 s10, s10, 0x2b0080
	s_addc_u32 s11, s11, 0
	s_add_i32 m0, s36, 0xc000
	ds_read_b128 v[172:175], v139
	ds_read_b128 v[176:179], v139 offset:1024
	ds_read_b128 v[180:183], v139 offset:2048
	ds_read_b128 v[184:187], v139 offset:3072
	ds_read_b128 v[188:191], v139 offset:4096
	ds_read_b128 v[192:195], v139 offset:5120
	ds_read_b128 v[196:199], v139 offset:6144
	ds_read_b128 v[200:203], v139 offset:7168
	global_load_lds_dwordx4 v128, s[10:11]
	s_add_i32 m0, s36, 0xe000
	s_nop 0
	global_load_lds_dwordx4 v130, s[10:11]
	s_waitcnt vmcnt(8)
	s_waitcnt lgkmcnt(0)
	s_barrier
	s_setprio 1
	s_waitcnt lgkmcnt(0)
	v_mfma_f32_16x16x32_bf16 v[124:127], v[140:143], v[172:175], v[124:127]
	v_mfma_f32_16x16x32_bf16 v[120:123], v[148:151], v[172:175], v[120:123]
	v_mfma_f32_16x16x32_bf16 v[112:115], v[140:143], v[180:183], v[112:115]
	v_mfma_f32_16x16x32_bf16 v[104:107], v[148:151], v[180:183], v[104:107]
	v_mfma_f32_16x16x32_bf16 v[96:99], v[140:143], v[188:191], v[96:99]
	v_mfma_f32_16x16x32_bf16 v[88:91], v[148:151], v[188:191], v[88:91]
	v_mfma_f32_16x16x32_bf16 v[80:83], v[140:143], v[196:199], v[80:83]
	v_mfma_f32_16x16x32_bf16 v[72:75], v[148:151], v[196:199], v[72:75]
	v_mfma_f32_16x16x32_bf16 v[124:127], v[144:147], v[176:179], v[124:127]
	v_mfma_f32_16x16x32_bf16 v[120:123], v[152:155], v[176:179], v[120:123]
	v_mfma_f32_16x16x32_bf16 v[112:115], v[144:147], v[184:187], v[112:115]
	v_mfma_f32_16x16x32_bf16 v[104:107], v[152:155], v[184:187], v[104:107]
	v_mfma_f32_16x16x32_bf16 v[96:99], v[144:147], v[192:195], v[96:99]
	v_mfma_f32_16x16x32_bf16 v[88:91], v[152:155], v[192:195], v[88:91]
	v_mfma_f32_16x16x32_bf16 v[80:83], v[144:147], v[200:203], v[80:83]
	v_mfma_f32_16x16x32_bf16 v[72:75], v[152:155], v[200:203], v[72:75]
	s_setprio 0
	s_setprio 1
	v_mfma_f32_16x16x32_bf16 v[116:119], v[156:159], v[172:175], v[116:119]
	v_mfma_f32_16x16x32_bf16 v[108:111], v[164:167], v[172:175], v[108:111]
	v_mfma_f32_16x16x32_bf16 v[100:103], v[156:159], v[180:183], v[100:103]
	v_mfma_f32_16x16x32_bf16 v[92:95], v[164:167], v[180:183], v[92:95]
	v_mfma_f32_16x16x32_bf16 v[84:87], v[156:159], v[188:191], v[84:87]
	v_mfma_f32_16x16x32_bf16 v[76:79], v[164:167], v[188:191], v[76:79]
	v_mfma_f32_16x16x32_bf16 v[68:71], v[156:159], v[196:199], v[68:71]
	v_mfma_f32_16x16x32_bf16 v[64:67], v[164:167], v[196:199], v[64:67]
	v_mfma_f32_16x16x32_bf16 v[116:119], v[160:163], v[176:179], v[116:119]
	v_mfma_f32_16x16x32_bf16 v[108:111], v[168:171], v[176:179], v[108:111]
	v_mfma_f32_16x16x32_bf16 v[100:103], v[160:163], v[184:187], v[100:103]
	v_mfma_f32_16x16x32_bf16 v[92:95], v[168:171], v[184:187], v[92:95]
	v_mfma_f32_16x16x32_bf16 v[84:87], v[160:163], v[192:195], v[84:87]
	v_mfma_f32_16x16x32_bf16 v[76:79], v[168:171], v[192:195], v[76:79]
	v_mfma_f32_16x16x32_bf16 v[68:71], v[160:163], v[200:203], v[68:71]
	v_mfma_f32_16x16x32_bf16 v[64:67], v[168:171], v[200:203], v[64:67]
	s_setprio 0
	s_barrier
	s_add_i32 s10, s46, s31
	s_mov_b32 m0, s10
	ds_read_b128 v[172:175], v139 offset:16384
	ds_read_b128 v[176:179], v139 offset:17408
	ds_read_b128 v[180:183], v139 offset:18432
	ds_read_b128 v[184:187], v139 offset:19456
	ds_read_b128 v[188:191], v139 offset:20480
	ds_read_b128 v[192:195], v139 offset:21504
	ds_read_b128 v[196:199], v139 offset:22528
	ds_read_b128 v[200:203], v139 offset:23552
	global_load_lds_dwordx4 v128, s[26:27]
	s_add_i32 m0, s10, 0x2000
	s_add_u32 s10, s26, 0x2b0000
	s_addc_u32 s11, s27, 0
	s_add_i32 s55, s47, s31
	global_load_lds_dwordx4 v130, s[26:27]
	s_mov_b32 m0, s55
	s_nop 0
	global_load_lds_dwordx4 v128, s[10:11]
	s_add_i32 m0, s55, 0x2000
	s_nop 0
	global_load_lds_dwordx4 v130, s[10:11]
	s_mov_b32 m0, s36
	s_nop 0
	global_load_lds_dwordx4 v128, s[28:29]
	s_mov_b32 m0, s37
	s_nop 0
	global_load_lds_dwordx4 v130, s[28:29]
	s_waitcnt vmcnt(8)
	s_waitcnt lgkmcnt(0)
	s_barrier
	s_setprio 1
	s_waitcnt lgkmcnt(0)
	v_mfma_f32_16x16x32_bf16 v[60:63], v[140:143], v[172:175], v[60:63]
	v_mfma_f32_16x16x32_bf16 v[56:59], v[148:151], v[172:175], v[56:59]
	v_mfma_f32_16x16x32_bf16 v[48:51], v[140:143], v[180:183], v[48:51]
	v_mfma_f32_16x16x32_bf16 v[40:43], v[148:151], v[180:183], v[40:43]
	v_mfma_f32_16x16x32_bf16 v[32:35], v[140:143], v[188:191], v[32:35]
	v_mfma_f32_16x16x32_bf16 v[24:27], v[148:151], v[188:191], v[24:27]
	v_mfma_f32_16x16x32_bf16 v[16:19], v[140:143], v[196:199], v[16:19]
	v_mfma_f32_16x16x32_bf16 v[8:11], v[148:151], v[196:199], v[8:11]
	v_mfma_f32_16x16x32_bf16 v[60:63], v[144:147], v[176:179], v[60:63]
	v_mfma_f32_16x16x32_bf16 v[56:59], v[152:155], v[176:179], v[56:59]
	v_mfma_f32_16x16x32_bf16 v[48:51], v[144:147], v[184:187], v[48:51]
	v_mfma_f32_16x16x32_bf16 v[40:43], v[152:155], v[184:187], v[40:43]
	v_mfma_f32_16x16x32_bf16 v[32:35], v[144:147], v[192:195], v[32:35]
	v_mfma_f32_16x16x32_bf16 v[24:27], v[152:155], v[192:195], v[24:27]
	v_mfma_f32_16x16x32_bf16 v[16:19], v[144:147], v[200:203], v[16:19]
	v_mfma_f32_16x16x32_bf16 v[8:11], v[152:155], v[200:203], v[8:11]
	s_setprio 0
	s_setprio 1
	v_mfma_f32_16x16x32_bf16 v[52:55], v[156:159], v[172:175], v[52:55]
	v_mfma_f32_16x16x32_bf16 v[44:47], v[164:167], v[172:175], v[44:47]
	v_mfma_f32_16x16x32_bf16 v[36:39], v[156:159], v[180:183], v[36:39]
	v_mfma_f32_16x16x32_bf16 v[28:31], v[164:167], v[180:183], v[28:31]
	v_mfma_f32_16x16x32_bf16 v[20:23], v[156:159], v[188:191], v[20:23]
	v_mfma_f32_16x16x32_bf16 v[12:15], v[164:167], v[188:191], v[12:15]
	v_mfma_f32_16x16x32_bf16 v[4:7], v[156:159], v[196:199], v[4:7]
	v_mfma_f32_16x16x32_bf16 v[0:3], v[164:167], v[196:199], v[0:3]
	v_mfma_f32_16x16x32_bf16 v[52:55], v[160:163], v[176:179], v[52:55]
	v_mfma_f32_16x16x32_bf16 v[44:47], v[168:171], v[176:179], v[44:47]
	v_mfma_f32_16x16x32_bf16 v[36:39], v[160:163], v[184:187], v[36:39]
	v_mfma_f32_16x16x32_bf16 v[28:31], v[168:171], v[184:187], v[28:31]
	v_mfma_f32_16x16x32_bf16 v[20:23], v[160:163], v[192:195], v[20:23]
	v_mfma_f32_16x16x32_bf16 v[12:15], v[168:171], v[192:195], v[12:15]
	v_mfma_f32_16x16x32_bf16 v[4:7], v[160:163], v[200:203], v[4:7]
	v_mfma_f32_16x16x32_bf16 v[0:3], v[168:171], v[200:203], v[0:3]
	s_setprio 0
	s_barrier
; #define PG8_WAIT_V(n) asm volatile("s_waitcnt vmcnt(" #n ")" ::: "memory")
; #define PG8_WAIT_L(n) asm volatile("s_waitcnt lgkmcnt(" #n ")" ::: "memory")
; #define PG8_BAR __builtin_amdgcn_s_barrier()
; #define PG8_SCHED __builtin_amdgcn_sched_barrier(0)
;     ...
;             PG8_LDB(B0, 1, 0); PG8_LDB(B1, 1, 1); PG8_SCHED; PG8_LDA(At, 1, 0); PG8_STAGE(PG8_SA(0, 1), a2 + hstepA, voffA);
;             PG8_WAIT_V(8); PG8_WAIT_L(0); PG8_BAR; PG8_MMA(0, 0, At, B0); PG8_MMA(0, 1, At, B1); PG8_BAR; PG8_SCHED;
;             if constexpr (!HALFU) PG8_LDA(At, 1, 1); PG8_STAGE(PG8_SB(1, 0), b3, voffB); PG8_STAGE(PG8_SB(1, 1), b3 + hstep, voffB); PG8_STAGE(PG8_SA(1, 0), a3, voffA);
;             PG8_WAIT_V(8); PG8_WAIT_L(0); PG8_BAR; if constexpr (!HALFU) { PG8_MMA(1, 0, At, B0); PG8_MMA(1, 1, At, B1); } PG8_BAR; PG8_SCHED;
	s_add_i32 s55, 0, 0x18000
	s_add_i32 s56, 0, 0x1c000
	v_add_u32_e32 v152, s55, v136
	v_add_u32_e32 v168, s56, v136
	ds_read_b128 v[140:143], v152
	ds_read_b128 v[144:147], v152 offset:1024
	ds_read_b128 v[148:151], v152 offset:2048
	ds_read_b128 v[152:155], v152 offset:3072
	ds_read_b128 v[156:159], v168
	ds_read_b128 v[160:163], v168 offset:1024
	ds_read_b128 v[164:167], v168 offset:2048
	ds_read_b128 v[168:171], v168 offset:3072
	s_add_u32 s10, s28, 0x2b0000
	s_addc_u32 s11, s29, 0
	s_mov_b32 m0, s38
	ds_read_b128 v[172:175], v139 offset:32768
	ds_read_b128 v[176:179], v139 offset:33792
	ds_read_b128 v[180:183], v139 offset:34816
	ds_read_b128 v[184:187], v139 offset:35840
	ds_read_b128 v[188:191], v139 offset:36864
	ds_read_b128 v[192:195], v139 offset:37888
	ds_read_b128 v[196:199], v139 offset:38912
	ds_read_b128 v[200:203], v139 offset:39936
	global_load_lds_dwordx4 v128, s[10:11]
	s_mov_b32 m0, s39
	s_nop 0
	global_load_lds_dwordx4 v130, s[10:11]
	s_waitcnt vmcnt(8)
	s_waitcnt lgkmcnt(0)
	s_barrier
	s_setprio 1
	s_waitcnt lgkmcnt(0)
	v_mfma_f32_16x16x32_bf16 v[124:127], v[140:143], v[172:175], v[124:127]
	v_mfma_f32_16x16x32_bf16 v[120:123], v[148:151], v[172:175], v[120:123]
	v_mfma_f32_16x16x32_bf16 v[112:115], v[140:143], v[180:183], v[112:115]
	v_mfma_f32_16x16x32_bf16 v[104:107], v[148:151], v[180:183], v[104:107]
	v_mfma_f32_16x16x32_bf16 v[96:99], v[140:143], v[188:191], v[96:99]
	v_mfma_f32_16x16x32_bf16 v[88:91], v[148:151], v[188:191], v[88:91]
	v_mfma_f32_16x16x32_bf16 v[80:83], v[140:143], v[196:199], v[80:83]
	v_mfma_f32_16x16x32_bf16 v[72:75], v[148:151], v[196:199], v[72:75]
	v_mfma_f32_16x16x32_bf16 v[124:127], v[144:147], v[176:179], v[124:127]
	v_mfma_f32_16x16x32_bf16 v[120:123], v[152:155], v[176:179], v[120:123]
	v_mfma_f32_16x16x32_bf16 v[112:115], v[144:147], v[184:187], v[112:115]
	v_mfma_f32_16x16x32_bf16 v[104:107], v[152:155], v[184:187], v[104:107]
	v_mfma_f32_16x16x32_bf16 v[96:99], v[144:147], v[192:195], v[96:99]
	v_mfma_f32_16x16x32_bf16 v[88:91], v[152:155], v[192:195], v[88:91]
	v_mfma_f32_16x16x32_bf16 v[80:83], v[144:147], v[200:203], v[80:83]
	v_mfma_f32_16x16x32_bf16 v[72:75], v[152:155], v[200:203], v[72:75]
	s_setprio 0
	s_setprio 1
	v_mfma_f32_16x16x32_bf16 v[116:119], v[156:159], v[172:175], v[116:119]
	v_mfma_f32_16x16x32_bf16 v[108:111], v[164:167], v[172:175], v[108:111]
	v_mfma_f32_16x16x32_bf16 v[100:103], v[156:159], v[180:183], v[100:103]
	v_mfma_f32_16x16x32_bf16 v[92:95], v[164:167], v[180:183], v[92:95]
	v_mfma_f32_16x16x32_bf16 v[84:87], v[156:159], v[188:191], v[84:87]
	v_mfma_f32_16x16x32_bf16 v[76:79], v[164:167], v[188:191], v[76:79]
	v_mfma_f32_16x16x32_bf16 v[68:71], v[156:159], v[196:199], v[68:71]
	v_mfma_f32_16x16x32_bf16 v[64:67], v[164:167], v[196:199], v[64:67]
	v_mfma_f32_16x16x32_bf16 v[116:119], v[160:163], v[176:179], v[116:119]
	v_mfma_f32_16x16x32_bf16 v[108:111], v[168:171], v[176:179], v[108:111]
	v_mfma_f32_16x16x32_bf16 v[100:103], v[160:163], v[184:187], v[100:103]
	v_mfma_f32_16x16x32_bf16 v[92:95], v[168:171], v[184:187], v[92:95]
	v_mfma_f32_16x16x32_bf16 v[84:87], v[160:163], v[192:195], v[84:87]
	v_mfma_f32_16x16x32_bf16 v[76:79], v[168:171], v[192:195], v[76:79]
	v_mfma_f32_16x16x32_bf16 v[68:71], v[160:163], v[200:203], v[68:71]
	v_mfma_f32_16x16x32_bf16 v[64:67], v[168:171], v[200:203], v[64:67]
	s_setprio 0
	s_barrier
	s_add_u32 s10, s26, 0x80
	s_addc_u32 s11, s27, 0
	s_add_i32 s28, s55, s31
	s_mov_b32 m0, s28
	ds_read_b128 v[172:175], v139 offset:49152
	ds_read_b128 v[176:179], v139 offset:50176
	ds_read_b128 v[180:183], v139 offset:51200
	ds_read_b128 v[184:187], v139 offset:52224
	ds_read_b128 v[188:191], v139 offset:53248
	ds_read_b128 v[192:195], v139 offset:54272
	ds_read_b128 v[196:199], v139 offset:55296
	ds_read_b128 v[200:203], v139 offset:56320
	global_load_lds_dwordx4 v128, s[10:11]
	s_add_i32 m0, s28, 0x2000
	v_lshl_add_u64 v[204:205], s[10:11], 0, v[130:131]
	s_add_u32 s10, s26, 0x2b0080
	s_addc_u32 s11, s27, 0
	s_add_i32 s26, s56, s31
	global_load_lds_dwordx4 v[204:205], off
	s_mov_b32 m0, s26
	s_nop 0
	global_load_lds_dwordx4 v128, s[10:11]
	s_add_i32 m0, s26, 0x2000
	s_nop 0
	global_load_lds_dwordx4 v130, s[10:11]
	s_mov_b32 m0, s43
	s_nop 0
	global_load_lds_dwordx4 v128, s[24:25]
	s_mov_b32 m0, s44
	s_nop 0
	global_load_lds_dwordx4 v130, s[24:25]
	s_waitcnt vmcnt(8)
	s_waitcnt lgkmcnt(0)
	s_barrier
	s_setprio 1
	s_waitcnt lgkmcnt(0)
	v_mfma_f32_16x16x32_bf16 v[60:63], v[140:143], v[172:175], v[60:63]
	v_mfma_f32_16x16x32_bf16 v[56:59], v[148:151], v[172:175], v[56:59]
	v_mfma_f32_16x16x32_bf16 v[48:51], v[140:143], v[180:183], v[48:51]
	v_mfma_f32_16x16x32_bf16 v[40:43], v[148:151], v[180:183], v[40:43]
	v_mfma_f32_16x16x32_bf16 v[32:35], v[140:143], v[188:191], v[32:35]
	v_mfma_f32_16x16x32_bf16 v[24:27], v[148:151], v[188:191], v[24:27]
	v_mfma_f32_16x16x32_bf16 v[16:19], v[140:143], v[196:199], v[16:19]
	v_mfma_f32_16x16x32_bf16 v[8:11], v[148:151], v[196:199], v[8:11]
	v_mfma_f32_16x16x32_bf16 v[60:63], v[144:147], v[176:179], v[60:63]
	v_mfma_f32_16x16x32_bf16 v[56:59], v[152:155], v[176:179], v[56:59]
	v_mfma_f32_16x16x32_bf16 v[48:51], v[144:147], v[184:187], v[48:51]
	v_mfma_f32_16x16x32_bf16 v[40:43], v[152:155], v[184:187], v[40:43]
	v_mfma_f32_16x16x32_bf16 v[32:35], v[144:147], v[192:195], v[32:35]
	v_mfma_f32_16x16x32_bf16 v[24:27], v[152:155], v[192:195], v[24:27]
	v_mfma_f32_16x16x32_bf16 v[16:19], v[144:147], v[200:203], v[16:19]
	v_mfma_f32_16x16x32_bf16 v[8:11], v[152:155], v[200:203], v[8:11]
	s_setprio 0
	s_setprio 1
	v_mfma_f32_16x16x32_bf16 v[52:55], v[156:159], v[172:175], v[52:55]
	v_mfma_f32_16x16x32_bf16 v[44:47], v[164:167], v[172:175], v[44:47]
	v_mfma_f32_16x16x32_bf16 v[36:39], v[156:159], v[180:183], v[36:39]
	v_mfma_f32_16x16x32_bf16 v[28:31], v[164:167], v[180:183], v[28:31]
	v_mfma_f32_16x16x32_bf16 v[20:23], v[156:159], v[188:191], v[20:23]
	v_mfma_f32_16x16x32_bf16 v[12:15], v[164:167], v[188:191], v[12:15]
	v_mfma_f32_16x16x32_bf16 v[4:7], v[156:159], v[196:199], v[4:7]
	v_mfma_f32_16x16x32_bf16 v[0:3], v[164:167], v[196:199], v[0:3]
	v_mfma_f32_16x16x32_bf16 v[52:55], v[160:163], v[176:179], v[52:55]
	v_mfma_f32_16x16x32_bf16 v[44:47], v[168:171], v[176:179], v[44:47]
	v_mfma_f32_16x16x32_bf16 v[36:39], v[160:163], v[184:187], v[36:39]
	v_mfma_f32_16x16x32_bf16 v[28:31], v[168:171], v[184:187], v[28:31]
	v_mfma_f32_16x16x32_bf16 v[20:23], v[160:163], v[192:195], v[20:23]
	v_mfma_f32_16x16x32_bf16 v[12:15], v[168:171], v[192:195], v[12:15]
	v_mfma_f32_16x16x32_bf16 v[4:7], v[160:163], v[200:203], v[4:7]
	v_mfma_f32_16x16x32_bf16 v[0:3], v[168:171], v[200:203], v[0:3]
	s_setprio 0
	s_barrier
	s_add_i32 s54, s54, 2
	s_add_u32 s52, s52, 0x100
	s_addc_u32 s53, s53, 0
	s_cmpk_gt_u32 s54, 0xa9
	s_mov_b64 s[10:11], s[22:23]
	s_cbranch_scc0 .LBB0_793
	s_and_b64 vcc, exec, s[12:13]
	s_cbranch_vccz .LBB0_796
	s_barrier

; #define PG8_WAIT_V(n) asm volatile("s_waitcnt vmcnt(" #n ")" ::: "memory")
; #define PG8_BAR __builtin_amdgcn_s_barrier()
;     ...
;     if constexpr (SP2) {
;         PG8_STAGE(PG8_SB(0, 0), cB, voffB); PG8_STAGE(PG8_SB(0, 1), cB + hstep, voffB); PG8_STAGE(PG8_SA(0, 0), cA, voffA); PG8_STAGE(PG8_SA(0, 1), cA + hstepA, voffA);
;         if (wr == 1) PG8_BAR;
;         PG8_WAIT_V(2); PG8_BAR;
;         PG8_STAGE(PG8_SB(1, 0), cB + kstep, voffB); PG8_STAGE(PG8_SA(1, 0), cA + kstep, voffA); PG8_STAGE(PG8_SB(1, 1), cB + hstep + kstep, voffB);
;         PG8_WAIT_V(6); PG8_BAR;
.LBB0_3416:
	s_and_b32 s12, s12, 3
	s_and_b32 s17, s58, 0xffff
	s_and_b32 s9, s35, 0xffff
	s_ashr_i32 s48, s88, 31
	s_lshl_b32 s49, s8, 6
	s_lshl_b32 s14, s8, 13
	s_lshl_b32 s20, s12, 12
	s_add_u32 s18, s28, 0x80
	s_addc_u32 s19, s29, 0
	s_add_i32 m0, s43, 0x18000
	s_waitcnt vmcnt(2)
	s_barrier
	global_load_lds_dwordx4 v128, s[18:19]
	s_add_i32 m0, s43, 0x1a000
	v_lshl_add_u64 v[2:3], s[18:19], 0, v[130:131]
	s_add_u32 s18, s30, 0x80
	s_addc_u32 s19, s31, 0
	s_add_i32 s50, s43, 0x8000
	s_add_i32 s51, s43, 0xa000
	global_load_lds_dwordx4 v[2:3], off
	s_mov_b32 m0, s50
	s_add_u32 s6, s6, 0x80
	global_load_lds_dwordx4 v128, s[18:19]
	s_mov_b32 m0, s51
	s_addc_u32 s7, s7, 0
	global_load_lds_dwordx4 v130, s[18:19]
	s_add_i32 m0, s43, 0x1c000
	global_load_lds_dwordx4 v128, s[6:7]
	s_add_i32 m0, s43, 0x1e000
	s_sext_i32_i8 s11, s4
	global_load_lds_dwordx4 v130, s[6:7]
	v_and_b32_e32 v1, 48, v0
	v_lshlrev_b32_e32 v2, 6, v0
	s_movk_i32 s4, 0x3c0
	v_lshlrev_b32_e32 v0, 2, v0
	v_and_or_b32 v1, v2, s4, v1
	v_and_b32_e32 v0, 32, v0
	s_waitcnt vmcnt(6)
	s_cmpk_lt_u32 s5, 0x100
	v_bitop3_b32 v2, v1, s14, v0 bitop3:0xde
	v_bitop3_b32 v136, s20, v1, v0 bitop3:0xf6
	s_cselect_b64 s[6:7], -1, 0
	s_add_i32 s53, 0, 0x10000
	s_add_i32 s54, 0, 0x14000
	s_mov_b32 s19, 0x20000
	s_brev_b32 s18, 8
	s_mov_b32 s8, s34
	s_lshl_b32 s52, s12, 6
	v_mov_b64_e32 v[132:133], 0x400
	v_mov_b64_e32 v[134:135], 0x3ff
	v_add_u32_e32 v137, s53, v136
	v_add_u32_e32 v138, s54, v136
	v_add_u32_e32 v139, 0, v2
	v_mov_b32_e32 v140, 0x7f7f7f7f
	s_mov_b32 s12, 0x3fb504f3
	s_mov_b32 s14, 0x3a800000
	s_barrier
	s_branch .LBB0_3419

; #define PG8_WAIT_V(n) asm volatile("s_waitcnt vmcnt(" #n ")" ::: "memory")
; #define PG8_WAIT_L(n) asm volatile("s_waitcnt lgkmcnt(" #n ")" ::: "memory")
; #define PG8_BAR __builtin_amdgcn_s_barrier()
; #define PG8_SCHED __builtin_amdgcn_sched_barrier(0)
;     ...
;             PG8_LDB(B0, 0, 0); PG8_LDB(B1, 0, 1); PG8_SCHED; PG8_LDA(At, 0, 0); PG8_STAGE(PG8_SA(1, 1), a1 + hstepA, voffA);
;             PG8_WAIT_V(8); PG8_WAIT_L(0); PG8_BAR; PG8_MMA(0, 0, At, B0); PG8_MMA(0, 1, At, B1); PG8_BAR; PG8_SCHED;
;             if constexpr (!HALFU) PG8_LDA(At, 0, 1); PG8_STAGE(PG8_SB(0, 0), b2, voffB); PG8_STAGE(PG8_SB(0, 1), b2 + hstep, voffB); PG8_STAGE(PG8_SA(0, 0), a2, voffA);
;             PG8_WAIT_V(8); PG8_WAIT_L(0); PG8_BAR; if constexpr (!HALFU) { PG8_MMA(1, 0, At, B0); PG8_MMA(1, 1, At, B1); } PG8_BAR; PG8_SCHED;
.LBB0_3426:
	ds_read_b128 v[142:145], v137
	ds_read_b128 v[146:149], v137 offset:1024
	ds_read_b128 v[150:153], v137 offset:2048
	ds_read_b128 v[154:157], v137 offset:3072
	ds_read_b128 v[158:161], v138
	ds_read_b128 v[162:165], v138 offset:1024
	ds_read_b128 v[166:169], v138 offset:2048
	ds_read_b128 v[170:173], v138 offset:3072
	s_cmp_eq_u32 s62, 28
	s_cselect_b32 s38, s55, s57
	s_cselect_b32 s39, s23, s59
	s_cselect_b32 s36, s56, s60
	s_cselect_b32 s37, s21, s61
	s_add_u32 s30, s38, 0x80
	s_addc_u32 s31, s39, 0
	s_add_i32 m0, s43, 0xc000
	ds_read_b128 v[174:177], v139
	ds_read_b128 v[178:181], v139 offset:1024
	ds_read_b128 v[182:185], v139 offset:2048
	ds_read_b128 v[186:189], v139 offset:3072
	ds_read_b128 v[190:193], v139 offset:4096
	ds_read_b128 v[194:197], v139 offset:5120
	ds_read_b128 v[198:201], v139 offset:6144
	ds_read_b128 v[202:205], v139 offset:7168
	global_load_lds_dwordx4 v128, s[28:29]
	s_add_i32 m0, s43, 0xe000
	s_nop 0
	global_load_lds_dwordx4 v130, s[28:29]
	s_waitcnt vmcnt(8)
	s_waitcnt lgkmcnt(0)
	s_barrier
	s_setprio 1
	s_waitcnt lgkmcnt(0)
	v_mfma_scale_f32_16x16x128_f8f6f4 v[124:127], v[142:149], v[174:181], v[124:127], v140, v140 op_sel_hi:[0,0,0]
	v_mfma_scale_f32_16x16x128_f8f6f4 v[120:123], v[150:157], v[174:181], v[120:123], v140, v140 op_sel_hi:[0,0,0]
	v_mfma_scale_f32_16x16x128_f8f6f4 v[112:115], v[142:149], v[182:189], v[112:115], v140, v140 op_sel_hi:[0,0,0]
	v_mfma_scale_f32_16x16x128_f8f6f4 v[104:107], v[150:157], v[182:189], v[104:107], v140, v140 op_sel_hi:[0,0,0]
	v_mfma_scale_f32_16x16x128_f8f6f4 v[96:99], v[142:149], v[190:197], v[96:99], v140, v140 op_sel_hi:[0,0,0]
	v_mfma_scale_f32_16x16x128_f8f6f4 v[206:209], v[150:157], v[190:197], v[88:91], v140, v140 op_sel_hi:[0,0,0]
	v_mfma_scale_f32_16x16x128_f8f6f4 v[210:213], v[142:149], v[198:205], v[80:83], v140, v140 op_sel_hi:[0,0,0]
	v_mfma_scale_f32_16x16x128_f8f6f4 v[214:217], v[150:157], v[198:205], v[72:75], v140, v140 op_sel_hi:[0,0,0]
	s_setprio 0
	s_setprio 1
	v_mfma_scale_f32_16x16x128_f8f6f4 v[116:119], v[158:165], v[174:181], v[116:119], v140, v140 op_sel_hi:[0,0,0]
	v_mfma_scale_f32_16x16x128_f8f6f4 v[108:111], v[166:173], v[174:181], v[108:111], v140, v140 op_sel_hi:[0,0,0]
	v_mfma_scale_f32_16x16x128_f8f6f4 v[100:103], v[158:165], v[182:189], v[100:103], v140, v140 op_sel_hi:[0,0,0]
	v_mfma_scale_f32_16x16x128_f8f6f4 v[174:177], v[166:173], v[182:189], v[92:95], v140, v140 op_sel_hi:[0,0,0]
	v_mfma_scale_f32_16x16x128_f8f6f4 v[178:181], v[158:165], v[190:197], v[84:87], v140, v140 op_sel_hi:[0,0,0]
	v_mfma_scale_f32_16x16x128_f8f6f4 v[182:185], v[166:173], v[190:197], v[76:79], v140, v140 op_sel_hi:[0,0,0]
	v_mfma_scale_f32_16x16x128_f8f6f4 v[186:189], v[158:165], v[198:205], v[68:71], v140, v140 op_sel_hi:[0,0,0]
	v_mfma_scale_f32_16x16x128_f8f6f4 v[190:193], v[166:173], v[198:205], v[64:67], v140, v140 op_sel_hi:[0,0,0]
	s_setprio 0
	s_barrier
	s_add_i32 s63, s53, s41
	s_mov_b32 m0, s63
	s_nop 1
	ds_read_b128 v[64:67], v139 offset:16384
	ds_read_b128 v[68:71], v139 offset:17408
	ds_read_b128 v[72:75], v139 offset:18432
	ds_read_b128 v[76:79], v139 offset:19456
	ds_read_b128 v[80:83], v139 offset:20480
	ds_read_b128 v[84:87], v139 offset:21504
	ds_read_b128 v[88:91], v139 offset:22528
	ds_read_b128 v[92:95], v139 offset:23552
	global_load_lds_dwordx4 v128, s[36:37]
	s_add_i32 m0, s63, 0x2000
	s_add_u32 s64, s36, 0x80000
	s_addc_u32 s65, s37, 0
	s_add_i32 s63, s54, s41
	global_load_lds_dwordx4 v130, s[36:37]
	s_mov_b32 m0, s63
	s_nop 0
	global_load_lds_dwordx4 v128, s[64:65]
	s_add_i32 m0, s63, 0x2000
	s_nop 0
	global_load_lds_dwordx4 v130, s[64:65]
	s_mov_b32 m0, s43
	s_nop 0
	global_load_lds_dwordx4 v128, s[38:39]
	s_mov_b32 m0, s44
	s_nop 0
	global_load_lds_dwordx4 v130, s[38:39]
	s_waitcnt vmcnt(8)
	s_waitcnt lgkmcnt(0)
	s_barrier
	s_setprio 1
	s_waitcnt lgkmcnt(0)
	v_mfma_scale_f32_16x16x128_f8f6f4 v[60:63], v[142:149], v[64:71], v[60:63], v140, v140 op_sel_hi:[0,0,0]
	v_mfma_scale_f32_16x16x128_f8f6f4 v[56:59], v[150:157], v[64:71], v[56:59], v140, v140 op_sel_hi:[0,0,0]
	v_mfma_scale_f32_16x16x128_f8f6f4 v[48:51], v[142:149], v[72:79], v[48:51], v140, v140 op_sel_hi:[0,0,0]
	v_mfma_scale_f32_16x16x128_f8f6f4 v[194:197], v[150:157], v[72:79], v[40:43], v140, v140 op_sel_hi:[0,0,0]
	v_mfma_scale_f32_16x16x128_f8f6f4 v[198:201], v[142:149], v[80:87], v[32:35], v140, v140 op_sel_hi:[0,0,0]
	v_mfma_scale_f32_16x16x128_f8f6f4 v[202:205], v[150:157], v[80:87], v[24:27], v140, v140 op_sel_hi:[0,0,0]
	v_mfma_scale_f32_16x16x128_f8f6f4 v[218:221], v[142:149], v[88:95], v[16:19], v140, v140 op_sel_hi:[0,0,0]
	v_mfma_scale_f32_16x16x128_f8f6f4 v[222:225], v[150:157], v[88:95], v[8:11], v140, v140 op_sel_hi:[0,0,0]
	s_setprio 0
	s_setprio 1
	v_mfma_scale_f32_16x16x128_f8f6f4 v[52:55], v[158:165], v[64:71], v[52:55], v140, v140 op_sel_hi:[0,0,0]
	v_mfma_scale_f32_16x16x128_f8f6f4 v[226:229], v[166:173], v[64:71], v[44:47], v140, v140 op_sel_hi:[0,0,0]
	v_mfma_scale_f32_16x16x128_f8f6f4 v[230:233], v[158:165], v[72:79], v[36:39], v140, v140 op_sel_hi:[0,0,0]
	v_mfma_scale_f32_16x16x128_f8f6f4 v[234:237], v[166:173], v[72:79], v[28:31], v140, v140 op_sel_hi:[0,0,0]
	v_mfma_scale_f32_16x16x128_f8f6f4 v[238:241], v[158:165], v[80:87], v[20:23], v140, v140 op_sel_hi:[0,0,0]
	v_mfma_scale_f32_16x16x128_f8f6f4 v[242:245], v[166:173], v[80:87], v[12:15], v140, v140 op_sel_hi:[0,0,0]
	v_mfma_scale_f32_16x16x128_f8f6f4 v[246:249], v[158:165], v[88:95], v[4:7], v140, v140 op_sel_hi:[0,0,0]
	v_mfma_scale_f32_16x16x128_f8f6f4 v[250:253], v[166:173], v[88:95], v[0:3], v140, v140 op_sel_hi:[0,0,0]
	s_setprio 0
	s_barrier
; #define PG8_WAIT_V(n) asm volatile("s_waitcnt vmcnt(" #n ")" ::: "memory")
; #define PG8_WAIT_L(n) asm volatile("s_waitcnt lgkmcnt(" #n ")" ::: "memory")
; #define PG8_BAR __builtin_amdgcn_s_barrier()
; #define PG8_SCHED __builtin_amdgcn_sched_barrier(0)
;     ...
;             PG8_LDB(B0, 1, 0); PG8_LDB(B1, 1, 1); PG8_SCHED; PG8_LDA(At, 1, 0); PG8_STAGE(PG8_SA(0, 1), a2 + hstepA, voffA);
;             PG8_WAIT_V(8); PG8_WAIT_L(0); PG8_BAR; PG8_MMA(0, 0, At, B0); PG8_MMA(0, 1, At, B1); PG8_BAR; PG8_SCHED;
;             if constexpr (!HALFU) PG8_LDA(At, 1, 1); PG8_STAGE(PG8_SB(1, 0), b3, voffB); PG8_STAGE(PG8_SB(1, 1), b3 + hstep, voffB); PG8_STAGE(PG8_SA(1, 0), a3, voffA);
;             PG8_WAIT_V(8); PG8_WAIT_L(0); PG8_BAR; if constexpr (!HALFU) { PG8_MMA(1, 0, At, B0); PG8_MMA(1, 1, At, B1); } PG8_BAR; PG8_SCHED;
	s_add_i32 s63, 0, 0x18000
	s_add_i32 s64, 0, 0x1c000
	s_nop 0
	v_add_u32_e32 v12, s63, v136
	v_add_u32_e32 v16, s64, v136
	ds_read_b128 v[0:3], v12
	ds_read_b128 v[4:7], v12 offset:1024
	ds_read_b128 v[8:11], v12 offset:2048
	ds_read_b128 v[12:15], v12 offset:3072
	ds_read_b128 v[142:145], v16
	ds_read_b128 v[146:149], v16 offset:1024
	ds_read_b128 v[150:153], v16 offset:2048
	ds_read_b128 v[154:157], v16 offset:3072
	s_add_u32 s38, s38, 0x80000
	s_addc_u32 s39, s39, 0
	s_mov_b32 m0, s45
	ds_read_b128 v[16:19], v139 offset:32768
	ds_read_b128 v[20:23], v139 offset:33792
	ds_read_b128 v[24:27], v139 offset:34816
	ds_read_b128 v[28:31], v139 offset:35840
	ds_read_b128 v[32:35], v139 offset:36864
	ds_read_b128 v[36:39], v139 offset:37888
	ds_read_b128 v[40:43], v139 offset:38912
	ds_read_b128 v[44:47], v139 offset:39936
	global_load_lds_dwordx4 v128, s[38:39]
	s_mov_b32 m0, s46
	s_nop 0
	global_load_lds_dwordx4 v130, s[38:39]
	s_waitcnt vmcnt(8)
	s_waitcnt lgkmcnt(0)
	s_barrier
	s_setprio 1
	s_waitcnt lgkmcnt(0)
	v_mfma_scale_f32_16x16x128_f8f6f4 v[124:127], v[0:7], v[16:23], v[124:127], v140, v140 op_sel_hi:[0,0,0]
	v_mfma_scale_f32_16x16x128_f8f6f4 v[120:123], v[8:15], v[16:23], v[120:123], v140, v140 op_sel_hi:[0,0,0]
	v_mfma_scale_f32_16x16x128_f8f6f4 v[112:115], v[0:7], v[24:31], v[112:115], v140, v140 op_sel_hi:[0,0,0]
	v_mfma_scale_f32_16x16x128_f8f6f4 v[104:107], v[8:15], v[24:31], v[104:107], v140, v140 op_sel_hi:[0,0,0]
	v_mfma_scale_f32_16x16x128_f8f6f4 v[96:99], v[0:7], v[32:39], v[96:99], v140, v140 op_sel_hi:[0,0,0]
	v_mfma_scale_f32_16x16x128_f8f6f4 v[88:91], v[8:15], v[32:39], v[206:209], v140, v140 op_sel_hi:[0,0,0]
	v_mfma_scale_f32_16x16x128_f8f6f4 v[80:83], v[0:7], v[40:47], v[210:213], v140, v140 op_sel_hi:[0,0,0]
	v_mfma_scale_f32_16x16x128_f8f6f4 v[72:75], v[8:15], v[40:47], v[214:217], v140, v140 op_sel_hi:[0,0,0]
	s_setprio 0
	s_setprio 1
	v_mfma_scale_f32_16x16x128_f8f6f4 v[116:119], v[142:149], v[16:23], v[116:119], v140, v140 op_sel_hi:[0,0,0]
	v_mfma_scale_f32_16x16x128_f8f6f4 v[108:111], v[150:157], v[16:23], v[108:111], v140, v140 op_sel_hi:[0,0,0]
	v_mfma_scale_f32_16x16x128_f8f6f4 v[100:103], v[142:149], v[24:31], v[100:103], v140, v140 op_sel_hi:[0,0,0]
	v_mfma_scale_f32_16x16x128_f8f6f4 v[92:95], v[150:157], v[24:31], v[174:177], v140, v140 op_sel_hi:[0,0,0]
	v_mfma_scale_f32_16x16x128_f8f6f4 v[84:87], v[142:149], v[32:39], v[178:181], v140, v140 op_sel_hi:[0,0,0]
	v_mfma_scale_f32_16x16x128_f8f6f4 v[76:79], v[150:157], v[32:39], v[182:185], v140, v140 op_sel_hi:[0,0,0]
	v_mfma_scale_f32_16x16x128_f8f6f4 v[68:71], v[142:149], v[40:47], v[186:189], v140, v140 op_sel_hi:[0,0,0]
	v_mfma_scale_f32_16x16x128_f8f6f4 v[64:67], v[150:157], v[40:47], v[190:193], v140, v140 op_sel_hi:[0,0,0]
	s_setprio 0
	s_barrier
	s_add_u32 s38, s36, 0x80
	s_addc_u32 s39, s37, 0
	s_add_i32 s63, s63, s41
	s_mov_b32 m0, s63
	ds_read_b128 v[158:161], v139 offset:49152
	ds_read_b128 v[162:165], v139 offset:50176
	ds_read_b128 v[166:169], v139 offset:51200
	ds_read_b128 v[170:173], v139 offset:52224
	ds_read_b128 v[174:177], v139 offset:53248
	ds_read_b128 v[178:181], v139 offset:54272
	ds_read_b128 v[182:185], v139 offset:55296
	ds_read_b128 v[186:189], v139 offset:56320
	global_load_lds_dwordx4 v128, s[38:39]
	s_add_i32 m0, s63, 0x2000
	s_add_u32 s36, s36, 0x80080
	v_lshl_add_u64 v[16:17], s[38:39], 0, v[130:131]
	s_addc_u32 s37, s37, 0
	s_add_i32 s38, s64, s41
	global_load_lds_dwordx4 v[16:17], off
	s_mov_b32 m0, s38
	s_nop 0
	global_load_lds_dwordx4 v128, s[36:37]
	s_add_i32 m0, s38, 0x2000
	s_nop 0
	global_load_lds_dwordx4 v130, s[36:37]
	s_mov_b32 m0, s50
	s_nop 0
	global_load_lds_dwordx4 v128, s[30:31]
	s_mov_b32 m0, s51
	s_nop 0
	global_load_lds_dwordx4 v130, s[30:31]
	s_waitcnt vmcnt(8)
	s_waitcnt lgkmcnt(0)
	s_barrier
	s_setprio 1
	s_waitcnt lgkmcnt(0)
	v_mfma_scale_f32_16x16x128_f8f6f4 v[60:63], v[0:7], v[158:165], v[60:63], v140, v140 op_sel_hi:[0,0,0]
	v_mfma_scale_f32_16x16x128_f8f6f4 v[56:59], v[8:15], v[158:165], v[56:59], v140, v140 op_sel_hi:[0,0,0]
	v_mfma_scale_f32_16x16x128_f8f6f4 v[48:51], v[0:7], v[166:173], v[48:51], v140, v140 op_sel_hi:[0,0,0]
	v_mfma_scale_f32_16x16x128_f8f6f4 v[40:43], v[8:15], v[166:173], v[194:197], v140, v140 op_sel_hi:[0,0,0]
	v_mfma_scale_f32_16x16x128_f8f6f4 v[32:35], v[0:7], v[174:181], v[198:201], v140, v140 op_sel_hi:[0,0,0]
	v_mfma_scale_f32_16x16x128_f8f6f4 v[24:27], v[8:15], v[174:181], v[202:205], v140, v140 op_sel_hi:[0,0,0]
	v_mfma_scale_f32_16x16x128_f8f6f4 v[16:19], v[0:7], v[182:189], v[218:221], v140, v140 op_sel_hi:[0,0,0]
	v_mfma_scale_f32_16x16x128_f8f6f4 v[8:11], v[8:15], v[182:189], v[222:225], v140, v140 op_sel_hi:[0,0,0]
	s_setprio 0
	s_setprio 1
	v_mfma_scale_f32_16x16x128_f8f6f4 v[52:55], v[142:149], v[158:165], v[52:55], v140, v140 op_sel_hi:[0,0,0]
	v_mfma_scale_f32_16x16x128_f8f6f4 v[44:47], v[150:157], v[158:165], v[226:229], v140, v140 op_sel_hi:[0,0,0]
	v_mfma_scale_f32_16x16x128_f8f6f4 v[36:39], v[142:149], v[166:173], v[230:233], v140, v140 op_sel_hi:[0,0,0]
	v_mfma_scale_f32_16x16x128_f8f6f4 v[28:31], v[150:157], v[166:173], v[234:237], v140, v140 op_sel_hi:[0,0,0]
	v_mfma_scale_f32_16x16x128_f8f6f4 v[20:23], v[142:149], v[174:181], v[238:241], v140, v140 op_sel_hi:[0,0,0]
	v_mfma_scale_f32_16x16x128_f8f6f4 v[12:15], v[150:157], v[174:181], v[242:245], v140, v140 op_sel_hi:[0,0,0]
	v_mfma_scale_f32_16x16x128_f8f6f4 v[4:7], v[142:149], v[182:189], v[246:249], v140, v140 op_sel_hi:[0,0,0]
	v_mfma_scale_f32_16x16x128_f8f6f4 v[0:3], v[150:157], v[182:189], v[250:253], v140, v140 op_sel_hi:[0,0,0]
	s_setprio 0
	s_barrier
	s_add_i32 s62, s62, 2
	s_add_u32 s57, s57, 0x100
	s_addc_u32 s59, s59, 0
	s_add_u32 s60, s60, 0x100
	s_addc_u32 s61, s61, 0
	s_add_u32 s28, s28, 0x100
	s_addc_u32 s29, s29, 0
	s_cmp_gt_u32 s62, 29
	s_cbranch_scc0 .LBB0_3426
	s_and_b64 vcc, exec, s[6:7]
	s_cbranch_vccz .LBB0_3429
	s_barrier

; #define PG8_WAIT_V(n) asm volatile("s_waitcnt vmcnt(" #n ")" ::: "memory")
; #define PG8_BAR __builtin_amdgcn_s_barrier()
;     ...
;     const int aoff = lds_byte(wr * 64 + fr, fq * 8), boff = lds_byte(wc * 32 + fr, fq * 8);
;     ...
;         PG8_STAGE(PG8_SB(0, 0), cB, voffB); PG8_STAGE(PG8_SB(0, 1), cB + hstep, voffB); PG8_STAGE(PG8_SA(0, 0), cA, voffA); PG8_STAGE(PG8_SA(0, 1), cA + hstepA, voffA);
;         if (wr == 1) PG8_BAR;
;         PG8_WAIT_V(2); PG8_BAR;
;         PG8_STAGE(PG8_SB(1, 0), cB + kstep, voffB); PG8_STAGE(PG8_SA(1, 0), cA + kstep, voffA); PG8_STAGE(PG8_SB(1, 1), cB + hstep + kstep, voffB);
;         PG8_WAIT_V(6); PG8_BAR;
.LBB0_3626:
	s_and_b32 s14, s8, 3
	s_and_b32 s17, s58, 0xffff
	s_and_b32 s9, s35, 0xffff
	s_ashr_i32 s40, s88, 31
	s_lshl_b32 s41, s7, 6
	s_lshl_b32 s7, s7, 13
	s_lshl_b32 s13, s14, 12
	s_add_u32 s18, s10, 0x80
	s_addc_u32 s19, s11, 0
	s_add_i32 m0, s33, 0x18000
	s_waitcnt vmcnt(2)
	s_barrier
	global_load_lds_dwordx4 v128, s[18:19]
	s_add_i32 m0, s33, 0x1a000
	v_lshl_add_u64 v[2:3], s[18:19], 0, v[130:131]
	s_add_u32 s18, s24, 0x80
	s_addc_u32 s19, s25, 0
	s_add_i32 s42, s33, 0x8000
	s_add_i32 s43, s33, 0xa000
	global_load_lds_dwordx4 v[2:3], off
	s_mov_b32 m0, s42
	s_add_u32 s4, s4, 0x80
	global_load_lds_dwordx4 v128, s[18:19]
	s_mov_b32 m0, s43
	s_addc_u32 s5, s5, 0
	global_load_lds_dwordx4 v130, s[18:19]
	s_add_i32 m0, s33, 0x1c000
	global_load_lds_dwordx4 v128, s[4:5]
	s_add_i32 m0, s33, 0x1e000
	v_and_b32_e32 v1, 48, v0
	global_load_lds_dwordx4 v130, s[4:5]
	v_lshlrev_b32_e32 v2, 6, v0
	s_movk_i32 s4, 0x3c0
	v_lshlrev_b32_e32 v0, 2, v0
	v_and_or_b32 v1, v2, s4, v1
	v_and_b32_e32 v0, 32, v0
	s_waitcnt vmcnt(6)
	s_cmpk_lt_u32 s6, 0x100
	s_sext_i32_i8 s50, s12
	v_bitop3_b32 v2, v1, s7, v0 bitop3:0xde
	v_bitop3_b32 v136, s13, v1, v0 bitop3:0xf6
	s_cselect_b64 s[12:13], -1, 0
	s_add_i32 s45, 0, 0x10000
	s_add_i32 s46, 0, 0x14000
	s_mov_b32 s19, 0x20000
	s_brev_b32 s18, 8
	s_mov_b32 s8, s34
	s_lshl_b32 s44, s14, 6
	v_mov_b64_e32 v[132:133], 0x400
	v_mov_b64_e32 v[134:135], 0x3ff
	v_add_u32_e32 v137, s45, v136
	v_add_u32_e32 v138, s46, v136
	v_add_u32_e32 v139, 0, v2
	v_mov_b32_e32 v140, 0x7f7f7f7f
	s_mov_b32 s14, 0x3fb504f3
	s_mov_b32 s20, 0x3a000000
	s_barrier
	s_branch .LBB0_3629

; #define PG8_WAIT_V(n) asm volatile("s_waitcnt vmcnt(" #n ")" ::: "memory")
; #define PG8_WAIT_L(n) asm volatile("s_waitcnt lgkmcnt(" #n ")" ::: "memory")
; #define PG8_BAR __builtin_amdgcn_s_barrier()
; #define PG8_SCHED __builtin_amdgcn_sched_barrier(0)
;     ...
;             PG8_LDB(B0, 0, 0); PG8_LDB(B1, 0, 1); PG8_SCHED; PG8_LDA(At, 0, 0); PG8_STAGE(PG8_SA(1, 1), a1 + hstepA, voffA);
;             PG8_WAIT_V(8); PG8_WAIT_L(0); PG8_BAR; PG8_MMA(0, 0, At, B0); PG8_MMA(0, 1, At, B1); PG8_BAR; PG8_SCHED;
;             if constexpr (!HALFU) PG8_LDA(At, 0, 1); PG8_STAGE(PG8_SB(0, 0), b2, voffB); PG8_STAGE(PG8_SB(0, 1), b2 + hstep, voffB); PG8_STAGE(PG8_SA(0, 0), a2, voffA);
;             PG8_WAIT_V(8); PG8_WAIT_L(0); PG8_BAR; if constexpr (!HALFU) { PG8_MMA(1, 0, At, B0); PG8_MMA(1, 1, At, B1); } PG8_BAR; PG8_SCHED;
.LBB0_3640:
	ds_read_b128 v[142:145], v137
	ds_read_b128 v[146:149], v137 offset:1024
	ds_read_b128 v[150:153], v137 offset:2048
	ds_read_b128 v[154:157], v137 offset:3072
	ds_read_b128 v[158:161], v138
	ds_read_b128 v[162:165], v138 offset:1024
	ds_read_b128 v[166:169], v138 offset:2048
	ds_read_b128 v[170:173], v138 offset:3072
	s_cmpk_eq_i32 s55, 0x52
	s_cselect_b32 s28, s6, s51
	s_cselect_b32 s29, s7, s52
	s_cselect_b32 s26, s22, s53
	s_cselect_b32 s27, s23, s54
	s_add_u32 s24, s28, 0x80
	s_addc_u32 s25, s29, 0
	s_add_i32 m0, s33, 0xc000
	ds_read_b128 v[174:177], v139
	ds_read_b128 v[178:181], v139 offset:1024
	ds_read_b128 v[182:185], v139 offset:2048
	ds_read_b128 v[186:189], v139 offset:3072
	ds_read_b128 v[190:193], v139 offset:4096
	ds_read_b128 v[194:197], v139 offset:5120
	ds_read_b128 v[198:201], v139 offset:6144
	ds_read_b128 v[202:205], v139 offset:7168
	global_load_lds_dwordx4 v128, s[10:11]
	s_add_i32 m0, s33, 0xe000
	s_nop 0
	global_load_lds_dwordx4 v130, s[10:11]
	s_waitcnt vmcnt(8)
	s_waitcnt lgkmcnt(0)
	s_barrier
	s_setprio 1
	s_waitcnt lgkmcnt(0)
	v_mfma_scale_f32_16x16x128_f8f6f4 v[124:127], v[142:149], v[174:181], v[124:127], v140, v140 op_sel_hi:[0,0,0]
	v_mfma_scale_f32_16x16x128_f8f6f4 v[120:123], v[150:157], v[174:181], v[120:123], v140, v140 op_sel_hi:[0,0,0]
	v_mfma_scale_f32_16x16x128_f8f6f4 v[112:115], v[142:149], v[182:189], v[112:115], v140, v140 op_sel_hi:[0,0,0]
	v_mfma_scale_f32_16x16x128_f8f6f4 v[104:107], v[150:157], v[182:189], v[104:107], v140, v140 op_sel_hi:[0,0,0]
	v_mfma_scale_f32_16x16x128_f8f6f4 v[96:99], v[142:149], v[190:197], v[96:99], v140, v140 op_sel_hi:[0,0,0]
	v_mfma_scale_f32_16x16x128_f8f6f4 v[206:209], v[150:157], v[190:197], v[88:91], v140, v140 op_sel_hi:[0,0,0]
	v_mfma_scale_f32_16x16x128_f8f6f4 v[210:213], v[142:149], v[198:205], v[80:83], v140, v140 op_sel_hi:[0,0,0]
	v_mfma_scale_f32_16x16x128_f8f6f4 v[214:217], v[150:157], v[198:205], v[72:75], v140, v140 op_sel_hi:[0,0,0]
	s_setprio 0
	s_setprio 1
	v_mfma_scale_f32_16x16x128_f8f6f4 v[116:119], v[158:165], v[174:181], v[116:119], v140, v140 op_sel_hi:[0,0,0]
	v_mfma_scale_f32_16x16x128_f8f6f4 v[108:111], v[166:173], v[174:181], v[108:111], v140, v140 op_sel_hi:[0,0,0]
	v_mfma_scale_f32_16x16x128_f8f6f4 v[100:103], v[158:165], v[182:189], v[100:103], v140, v140 op_sel_hi:[0,0,0]
	v_mfma_scale_f32_16x16x128_f8f6f4 v[174:177], v[166:173], v[182:189], v[92:95], v140, v140 op_sel_hi:[0,0,0]
	v_mfma_scale_f32_16x16x128_f8f6f4 v[178:181], v[158:165], v[190:197], v[84:87], v140, v140 op_sel_hi:[0,0,0]
	v_mfma_scale_f32_16x16x128_f8f6f4 v[182:185], v[166:173], v[190:197], v[76:79], v140, v140 op_sel_hi:[0,0,0]
	v_mfma_scale_f32_16x16x128_f8f6f4 v[186:189], v[158:165], v[198:205], v[68:71], v140, v140 op_sel_hi:[0,0,0]
	v_mfma_scale_f32_16x16x128_f8f6f4 v[190:193], v[166:173], v[198:205], v[64:67], v140, v140 op_sel_hi:[0,0,0]
	s_setprio 0
	s_barrier
	s_add_i32 s56, s45, s30
	s_mov_b32 m0, s56
	s_nop 1
	ds_read_b128 v[64:67], v139 offset:16384
	ds_read_b128 v[68:71], v139 offset:17408
	ds_read_b128 v[72:75], v139 offset:18432
	ds_read_b128 v[76:79], v139 offset:19456
	ds_read_b128 v[80:83], v139 offset:20480
	ds_read_b128 v[84:87], v139 offset:21504
	ds_read_b128 v[88:91], v139 offset:22528
	ds_read_b128 v[92:95], v139 offset:23552
	global_load_lds_dwordx4 v128, s[26:27]
	s_add_i32 m0, s56, 0x2000
	s_add_u32 s56, s26, 0x158000
	s_addc_u32 s57, s27, 0
	s_add_i32 s58, s46, s30
	global_load_lds_dwordx4 v130, s[26:27]
	s_mov_b32 m0, s58
	s_nop 0
	global_load_lds_dwordx4 v128, s[56:57]
	s_add_i32 m0, s58, 0x2000
	s_nop 0
	global_load_lds_dwordx4 v130, s[56:57]
	s_mov_b32 m0, s33
	s_nop 0
	global_load_lds_dwordx4 v128, s[28:29]
	s_mov_b32 m0, s36
	s_nop 0
	global_load_lds_dwordx4 v130, s[28:29]
	s_waitcnt vmcnt(8)
	s_waitcnt lgkmcnt(0)
	s_barrier
	s_setprio 1
	s_waitcnt lgkmcnt(0)
	v_mfma_scale_f32_16x16x128_f8f6f4 v[60:63], v[142:149], v[64:71], v[60:63], v140, v140 op_sel_hi:[0,0,0]
	v_mfma_scale_f32_16x16x128_f8f6f4 v[56:59], v[150:157], v[64:71], v[56:59], v140, v140 op_sel_hi:[0,0,0]
	v_mfma_scale_f32_16x16x128_f8f6f4 v[48:51], v[142:149], v[72:79], v[48:51], v140, v140 op_sel_hi:[0,0,0]
	v_mfma_scale_f32_16x16x128_f8f6f4 v[194:197], v[150:157], v[72:79], v[40:43], v140, v140 op_sel_hi:[0,0,0]
	v_mfma_scale_f32_16x16x128_f8f6f4 v[198:201], v[142:149], v[80:87], v[32:35], v140, v140 op_sel_hi:[0,0,0]
	v_mfma_scale_f32_16x16x128_f8f6f4 v[202:205], v[150:157], v[80:87], v[24:27], v140, v140 op_sel_hi:[0,0,0]
	v_mfma_scale_f32_16x16x128_f8f6f4 v[218:221], v[142:149], v[88:95], v[16:19], v140, v140 op_sel_hi:[0,0,0]
	v_mfma_scale_f32_16x16x128_f8f6f4 v[222:225], v[150:157], v[88:95], v[8:11], v140, v140 op_sel_hi:[0,0,0]
	s_setprio 0
	s_setprio 1
	v_mfma_scale_f32_16x16x128_f8f6f4 v[52:55], v[158:165], v[64:71], v[52:55], v140, v140 op_sel_hi:[0,0,0]
	v_mfma_scale_f32_16x16x128_f8f6f4 v[226:229], v[166:173], v[64:71], v[44:47], v140, v140 op_sel_hi:[0,0,0]
	v_mfma_scale_f32_16x16x128_f8f6f4 v[230:233], v[158:165], v[72:79], v[36:39], v140, v140 op_sel_hi:[0,0,0]
	v_mfma_scale_f32_16x16x128_f8f6f4 v[234:237], v[166:173], v[72:79], v[28:31], v140, v140 op_sel_hi:[0,0,0]
	v_mfma_scale_f32_16x16x128_f8f6f4 v[238:241], v[158:165], v[80:87], v[20:23], v140, v140 op_sel_hi:[0,0,0]
	v_mfma_scale_f32_16x16x128_f8f6f4 v[242:245], v[166:173], v[80:87], v[12:15], v140, v140 op_sel_hi:[0,0,0]
	v_mfma_scale_f32_16x16x128_f8f6f4 v[246:249], v[158:165], v[88:95], v[4:7], v140, v140 op_sel_hi:[0,0,0]
	v_mfma_scale_f32_16x16x128_f8f6f4 v[250:253], v[166:173], v[88:95], v[0:3], v140, v140 op_sel_hi:[0,0,0]
	s_setprio 0
	s_barrier
; #define PG8_WAIT_V(n) asm volatile("s_waitcnt vmcnt(" #n ")" ::: "memory")
; #define PG8_WAIT_L(n) asm volatile("s_waitcnt lgkmcnt(" #n ")" ::: "memory")
; #define PG8_BAR __builtin_amdgcn_s_barrier()
; #define PG8_SCHED __builtin_amdgcn_sched_barrier(0)
;     ...
;         for (int t = 0; t < nt; t += 2) {
;             const bool last = (t == nt - 2);
;             const char* a1 = cA + (size_t)(t + 1) * kstep;
;             const char* a2 = last ? nA : cA + (size_t)(t + 2) * kstep; const char* b2 = last ? nB : cB + (size_t)(t + 2) * kstep;
;             const char* a3 = a2 + kstep; const char* b3 = b2 + kstep;
;     ...
;             PG8_LDB(B0, 1, 0); PG8_LDB(B1, 1, 1); PG8_SCHED; PG8_LDA(At, 1, 0); PG8_STAGE(PG8_SA(0, 1), a2 + hstepA, voffA);
;             PG8_WAIT_V(8); PG8_WAIT_L(0); PG8_BAR; PG8_MMA(0, 0, At, B0); PG8_MMA(0, 1, At, B1); PG8_BAR; PG8_SCHED;
;             if constexpr (!HALFU) PG8_LDA(At, 1, 1); PG8_STAGE(PG8_SB(1, 0), b3, voffB); PG8_STAGE(PG8_SB(1, 1), b3 + hstep, voffB); PG8_STAGE(PG8_SA(1, 0), a3, voffA);
;             PG8_WAIT_V(8); PG8_WAIT_L(0); PG8_BAR; if constexpr (!HALFU) { PG8_MMA(1, 0, At, B0); PG8_MMA(1, 1, At, B1); } PG8_BAR; PG8_SCHED;
	s_add_i32 s56, 0, 0x18000
	s_add_i32 s57, 0, 0x1c000
	s_nop 0
	v_add_u32_e32 v12, s56, v136
	v_add_u32_e32 v16, s57, v136
	ds_read_b128 v[0:3], v12
	ds_read_b128 v[4:7], v12 offset:1024
	ds_read_b128 v[8:11], v12 offset:2048
	ds_read_b128 v[12:15], v12 offset:3072
	ds_read_b128 v[142:145], v16
	ds_read_b128 v[146:149], v16 offset:1024
	ds_read_b128 v[150:153], v16 offset:2048
	ds_read_b128 v[154:157], v16 offset:3072
	s_add_u32 s28, s28, 0x158000
	s_addc_u32 s29, s29, 0
	s_mov_b32 m0, s37
	ds_read_b128 v[16:19], v139 offset:32768
	ds_read_b128 v[20:23], v139 offset:33792
	ds_read_b128 v[24:27], v139 offset:34816
	ds_read_b128 v[28:31], v139 offset:35840
	ds_read_b128 v[32:35], v139 offset:36864
	ds_read_b128 v[36:39], v139 offset:37888
	ds_read_b128 v[40:43], v139 offset:38912
	ds_read_b128 v[44:47], v139 offset:39936
	global_load_lds_dwordx4 v128, s[28:29]
	s_mov_b32 m0, s38
	s_nop 0
	global_load_lds_dwordx4 v130, s[28:29]
	s_waitcnt vmcnt(8)
	s_waitcnt lgkmcnt(0)
	s_barrier
	s_setprio 1
	s_waitcnt lgkmcnt(0)
	v_mfma_scale_f32_16x16x128_f8f6f4 v[124:127], v[0:7], v[16:23], v[124:127], v140, v140 op_sel_hi:[0,0,0]
	v_mfma_scale_f32_16x16x128_f8f6f4 v[120:123], v[8:15], v[16:23], v[120:123], v140, v140 op_sel_hi:[0,0,0]
	v_mfma_scale_f32_16x16x128_f8f6f4 v[112:115], v[0:7], v[24:31], v[112:115], v140, v140 op_sel_hi:[0,0,0]
	v_mfma_scale_f32_16x16x128_f8f6f4 v[104:107], v[8:15], v[24:31], v[104:107], v140, v140 op_sel_hi:[0,0,0]
	v_mfma_scale_f32_16x16x128_f8f6f4 v[96:99], v[0:7], v[32:39], v[96:99], v140, v140 op_sel_hi:[0,0,0]
	v_mfma_scale_f32_16x16x128_f8f6f4 v[88:91], v[8:15], v[32:39], v[206:209], v140, v140 op_sel_hi:[0,0,0]
	v_mfma_scale_f32_16x16x128_f8f6f4 v[80:83], v[0:7], v[40:47], v[210:213], v140, v140 op_sel_hi:[0,0,0]
	v_mfma_scale_f32_16x16x128_f8f6f4 v[72:75], v[8:15], v[40:47], v[214:217], v140, v140 op_sel_hi:[0,0,0]
	s_setprio 0
	s_setprio 1
	v_mfma_scale_f32_16x16x128_f8f6f4 v[116:119], v[142:149], v[16:23], v[116:119], v140, v140 op_sel_hi:[0,0,0]
	v_mfma_scale_f32_16x16x128_f8f6f4 v[108:111], v[150:157], v[16:23], v[108:111], v140, v140 op_sel_hi:[0,0,0]
	v_mfma_scale_f32_16x16x128_f8f6f4 v[100:103], v[142:149], v[24:31], v[100:103], v140, v140 op_sel_hi:[0,0,0]
	v_mfma_scale_f32_16x16x128_f8f6f4 v[92:95], v[150:157], v[24:31], v[174:177], v140, v140 op_sel_hi:[0,0,0]
	v_mfma_scale_f32_16x16x128_f8f6f4 v[84:87], v[142:149], v[32:39], v[178:181], v140, v140 op_sel_hi:[0,0,0]
	v_mfma_scale_f32_16x16x128_f8f6f4 v[76:79], v[150:157], v[32:39], v[182:185], v140, v140 op_sel_hi:[0,0,0]
	v_mfma_scale_f32_16x16x128_f8f6f4 v[68:71], v[142:149], v[40:47], v[186:189], v140, v140 op_sel_hi:[0,0,0]
	v_mfma_scale_f32_16x16x128_f8f6f4 v[64:67], v[150:157], v[40:47], v[190:193], v140, v140 op_sel_hi:[0,0,0]
	s_setprio 0
	s_barrier
	s_add_u32 s28, s26, 0x80
	s_addc_u32 s29, s27, 0
	s_add_i32 s56, s56, s30
	s_mov_b32 m0, s56
	ds_read_b128 v[158:161], v139 offset:49152
	ds_read_b128 v[162:165], v139 offset:50176
	ds_read_b128 v[166:169], v139 offset:51200
	ds_read_b128 v[170:173], v139 offset:52224
	ds_read_b128 v[174:177], v139 offset:53248
	ds_read_b128 v[178:181], v139 offset:54272
	ds_read_b128 v[182:185], v139 offset:55296
	ds_read_b128 v[186:189], v139 offset:56320
	global_load_lds_dwordx4 v128, s[28:29]
	s_add_i32 m0, s56, 0x2000
	s_add_u32 s26, s26, 0x158080
	v_lshl_add_u64 v[16:17], s[28:29], 0, v[130:131]
	s_addc_u32 s27, s27, 0
	s_add_i32 s28, s57, s30
	global_load_lds_dwordx4 v[16:17], off
	s_mov_b32 m0, s28
	s_nop 0
	global_load_lds_dwordx4 v128, s[26:27]
	s_add_i32 m0, s28, 0x2000
	s_nop 0
	global_load_lds_dwordx4 v130, s[26:27]
	s_mov_b32 m0, s42
	s_nop 0
	global_load_lds_dwordx4 v128, s[24:25]
	s_mov_b32 m0, s43
	s_nop 0
	global_load_lds_dwordx4 v130, s[24:25]
	s_waitcnt vmcnt(8)
	s_waitcnt lgkmcnt(0)
	s_barrier
	s_setprio 1
	s_waitcnt lgkmcnt(0)
	v_mfma_scale_f32_16x16x128_f8f6f4 v[60:63], v[0:7], v[158:165], v[60:63], v140, v140 op_sel_hi:[0,0,0]
	v_mfma_scale_f32_16x16x128_f8f6f4 v[56:59], v[8:15], v[158:165], v[56:59], v140, v140 op_sel_hi:[0,0,0]
	v_mfma_scale_f32_16x16x128_f8f6f4 v[48:51], v[0:7], v[166:173], v[48:51], v140, v140 op_sel_hi:[0,0,0]
	v_mfma_scale_f32_16x16x128_f8f6f4 v[40:43], v[8:15], v[166:173], v[194:197], v140, v140 op_sel_hi:[0,0,0]
	v_mfma_scale_f32_16x16x128_f8f6f4 v[32:35], v[0:7], v[174:181], v[198:201], v140, v140 op_sel_hi:[0,0,0]
	v_mfma_scale_f32_16x16x128_f8f6f4 v[24:27], v[8:15], v[174:181], v[202:205], v140, v140 op_sel_hi:[0,0,0]
	v_mfma_scale_f32_16x16x128_f8f6f4 v[16:19], v[0:7], v[182:189], v[218:221], v140, v140 op_sel_hi:[0,0,0]
	v_mfma_scale_f32_16x16x128_f8f6f4 v[8:11], v[8:15], v[182:189], v[222:225], v140, v140 op_sel_hi:[0,0,0]
	s_setprio 0
	s_setprio 1
	v_mfma_scale_f32_16x16x128_f8f6f4 v[52:55], v[142:149], v[158:165], v[52:55], v140, v140 op_sel_hi:[0,0,0]
	v_mfma_scale_f32_16x16x128_f8f6f4 v[44:47], v[150:157], v[158:165], v[226:229], v140, v140 op_sel_hi:[0,0,0]
	v_mfma_scale_f32_16x16x128_f8f6f4 v[36:39], v[142:149], v[166:173], v[230:233], v140, v140 op_sel_hi:[0,0,0]
	v_mfma_scale_f32_16x16x128_f8f6f4 v[28:31], v[150:157], v[166:173], v[234:237], v140, v140 op_sel_hi:[0,0,0]
	v_mfma_scale_f32_16x16x128_f8f6f4 v[20:23], v[142:149], v[174:181], v[238:241], v140, v140 op_sel_hi:[0,0,0]
	v_mfma_scale_f32_16x16x128_f8f6f4 v[12:15], v[150:157], v[174:181], v[242:245], v140, v140 op_sel_hi:[0,0,0]
	v_mfma_scale_f32_16x16x128_f8f6f4 v[4:7], v[142:149], v[182:189], v[246:249], v140, v140 op_sel_hi:[0,0,0]
	v_mfma_scale_f32_16x16x128_f8f6f4 v[0:3], v[150:157], v[182:189], v[250:253], v140, v140 op_sel_hi:[0,0,0]
	s_setprio 0
	s_barrier
	s_add_i32 s55, s55, 2
	s_add_u32 s51, s51, 0x100
	s_addc_u32 s52, s52, 0
	s_add_u32 s53, s53, 0x100
	s_addc_u32 s54, s54, 0
	s_add_u32 s10, s10, 0x100
	s_addc_u32 s11, s11, 0
	s_cmpk_gt_u32 s55, 0x53
	s_cbranch_scc0 .LBB0_3640
	s_and_b64 vcc, exec, s[12:13]
	s_cbranch_vccz .LBB0_3643
	s_barrier
